# LRU prefetch moved after look-back, pool window sums 2 rows in flight, P0 x-rows 8 loads in flight, LN tail gamma/beta loads hoisted
# speedup vs baseline: 1.0334x; 1.0095x over previous
; __device__ __forceinline__ unsigned pk2(float lo, float hi) { return f2bf(lo) | (f2bf(hi) << 16); }
; __device__ __forceinline__ void p0_prologue(LAS unsigned char* lds, const Params& p) {
;     ...
;     for (int m = gw; m < MT; m += NGW) {
;         const float* xr = (m < NP) ? p.in[0] + (size_t)m * DM : p.in[1] + (size_t)(m - NP) * DM;
;         unsigned long long* o8 = (unsigned long long*)(XB + (size_t)m * DM) + lane;
; #pragma unroll
;         for (int j = 0; j < 8; ++j) { const f32x4 v = *((const f32x4*)xr + lane + 64 * j); o8[64 * j] = (unsigned long long)pk2(v.x, v.y) | ((unsigned long long)pk2(v.z, v.w) << 32); }
;     }
.LBB0_81:
	s_or_b64 exec, exec, s[14:15]
	v_lshl_add_u64 v[18:19], v[10:11], 0, v[8:9]
	v_add_co_u32_e32 v14, vcc, s19, v18
	s_nop 1
	v_addc_co_u32_e32 v15, vcc, 0, v19, vcc
	global_load_dwordx4 v[100:103], v[18:19], off
	global_load_dwordx4 v[104:107], v[18:19], off offset:1024
	global_load_dwordx4 v[108:111], v[18:19], off offset:2048
	global_load_dwordx4 v[112:115], v[18:19], off offset:3072
	global_load_dwordx4 v[116:119], v[14:15], off
	global_load_dwordx4 v[120:123], v[14:15], off offset:1024
	global_load_dwordx4 v[124:127], v[14:15], off offset:2048
	global_load_dwordx4 v[128:131], v[14:15], off offset:3072
	v_lshlrev_b64 v[10:11], 12, v[12:13]
	v_lshl_add_u64 v[20:21], v[4:5], 0, v[10:11]
	v_lshl_add_u64 v[0:1], v[0:1], 0, s[6:7]
	v_lshl_add_u64 v[6:7], v[6:7], 0, s[10:11]
	v_cmp_lt_i32_e32 vcc, s20, v0
	s_or_b64 s[12:13], vcc, s[12:13]
	s_waitcnt vmcnt(7)
	v_cvt_pk_bf16_f32 v10, v100, v101
	v_cvt_pk_bf16_f32 v11, v102, v103
	global_store_dwordx2 v[20:21], v[10:11], off
	s_waitcnt vmcnt(7)
	v_cvt_pk_bf16_f32 v10, v104, v105
	v_cvt_pk_bf16_f32 v11, v106, v107
	global_store_dwordx2 v[20:21], v[10:11], off offset:512
	s_waitcnt vmcnt(7)
	v_cvt_pk_bf16_f32 v10, v108, v109
	v_cvt_pk_bf16_f32 v11, v110, v111
	global_store_dwordx2 v[20:21], v[10:11], off offset:1024
	s_waitcnt vmcnt(7)
	v_cvt_pk_bf16_f32 v10, v112, v113
	v_cvt_pk_bf16_f32 v11, v114, v115
	global_store_dwordx2 v[20:21], v[10:11], off offset:1536
	s_waitcnt vmcnt(7)
	v_cvt_pk_bf16_f32 v10, v116, v117
	v_cvt_pk_bf16_f32 v11, v118, v119
	global_store_dwordx2 v[20:21], v[10:11], off offset:2048
	s_waitcnt vmcnt(7)
	v_cvt_pk_bf16_f32 v10, v120, v121
	v_cvt_pk_bf16_f32 v11, v122, v123
	global_store_dwordx2 v[20:21], v[10:11], off offset:2560
	s_waitcnt vmcnt(7)
	v_cvt_pk_bf16_f32 v10, v124, v125
	v_cvt_pk_bf16_f32 v11, v126, v127
	global_store_dwordx2 v[20:21], v[10:11], off offset:3072
	s_waitcnt vmcnt(7)
	v_cvt_pk_bf16_f32 v10, v128, v129
	v_cvt_pk_bf16_f32 v11, v130, v131
	global_store_dwordx2 v[20:21], v[10:11], off offset:3584
	s_andn2_b64 exec, exec, s[12:13]
	s_cbranch_execz .LBB0_84

.LBB0_408:
	s_cmp_eq_u32 s100, 0
	s_cbranch_scc1 .Lpf_skip
	v_add_u32_e32 v0, s99, v226
	v_mov_b64_e32 v[50:51], s[74:75]
	v_mad_i64_i32 v[34:35], s[0:1], v0, s25, v[50:51]
	s_lshl_b32 s0, s98, 8
	v_and_b32_e32 v46, 0x7ff, v0
	s_and_b32 s0, s0, 0xf00
	s_mov_b32 s1, s80
	v_lshl_add_u64 v[34:35], v[34:35], 0, s[0:1]
	v_mov_b32_e32 v153, v1
	v_cmp_gt_u32_e32 vcc, 3, v46
	v_lshl_add_u64 v[42:43], v[34:35], 0, v[152:153]
	s_mov_b64 s[16:17], 0x1000
	v_cndmask_b32_e64 v35, -1, 0, vcc
	v_cndmask_b32_e64 v34, v220, 0, vcc
	v_cmp_gt_u32_e32 vcc, 2, v46
	v_lshl_add_u64 v[44:45], v[42:43], 0, s[16:17]
	s_movk_i32 s12, 0x1000
	v_cndmask_b32_e64 v37, -1, 0, vcc
	v_cndmask_b32_e64 v36, v221, 0, vcc
	v_cmp_eq_u32_e32 vcc, 0, v46
	v_lshl_add_u64 v[34:35], v[44:45], 0, v[34:35]
	v_lshl_add_u64 v[38:39], v[44:45], 0, v[36:37]
	v_cndmask_b32_e64 v47, -1, 0, vcc
	v_cndmask_b32_e64 v46, v222, 0, vcc
	v_lshl_add_u64 v[44:45], v[44:45], 0, v[46:47]
	v_add_co_u32_e32 v46, vcc, s12, v42
	v_add_u32_e32 v0, 32, v0
	s_nop 0
	v_addc_co_u32_e32 v47, vcc, 0, v43, vcc
	v_and_b32_e32 v62, 0x7ff, v0
	v_mad_i64_i32 v[50:51], s[14:15], v0, s25, v[50:51]
	v_lshl_add_u64 v[50:51], v[50:51], 0, s[0:1]
	v_cmp_gt_u32_e32 vcc, 3, v62
	v_lshl_add_u64 v[58:59], v[50:51], 0, v[152:153]
	v_lshl_add_u64 v[60:61], v[58:59], 0, s[16:17]
	v_cndmask_b32_e64 v51, -1, 0, vcc
	v_cndmask_b32_e64 v50, v220, 0, vcc
	v_cmp_gt_u32_e32 vcc, 2, v62
	v_lshl_add_u64 v[50:51], v[60:61], 0, v[50:51]
	global_load_dwordx4 v[34:37], v[34:35], off
	s_nop 0
	global_load_dwordx4 v[38:41], v[38:39], off
	v_cndmask_b32_e64 v53, -1, 0, vcc
	v_cndmask_b32_e64 v52, v221, 0, vcc
	v_cmp_eq_u32_e32 vcc, 0, v62
	v_lshl_add_u64 v[54:55], v[60:61], 0, v[52:53]
	global_load_dwordx4 v[42:45], v[44:45], off
	s_nop 0
	global_load_dwordx4 v[46:49], v[46:47], off
	v_cndmask_b32_e64 v63, -1, 0, vcc
	v_cndmask_b32_e64 v62, v222, 0, vcc
	v_lshl_add_u64 v[60:61], v[60:61], 0, v[62:63]
	v_add_co_u32_e32 v62, vcc, 0x1000, v58
	global_load_dwordx4 v[50:53], v[50:51], off
	s_nop 0
	global_load_dwordx4 v[54:57], v[54:55], off
	v_addc_co_u32_e32 v63, vcc, 0, v59, vcc
	global_load_dwordx4 v[58:61], v[60:61], off
	s_nop 0
	global_load_dwordx4 v[62:65], v[62:63], off

; __device__ __forceinline__ void mix_phase(LAS unsigned char* lds, const Params& p, const int layer) {
;     ...
;                 const int s_ = u >> 4, r0 = mix_tile_row0(s_);
;                 const bool prt = s_ < 128;
.LBB0_409:
	s_mov_b32 s100, 0
	s_ashr_i32 s6, s12, 4
	s_cmpk_lt_i32 s6, 0x80
	s_cselect_b64 s[42:43], -1, 0
	s_cmpk_gt_i32 s6, 0x7f
	s_cselect_b64 s[0:1], -1, 0
	s_mov_b64 s[20:21], -1
	s_and_b64 vcc, exec, s[0:1]
	s_cbranch_vccz .LBB0_411
	s_lshl_b32 s7, s6, 6
	s_mov_b64 s[20:21], 0

; __device__ __forceinline__ void mix_phase(LAS unsigned char* lds, const Params& p, const int layer) {
;     ...
;                     if (u + 2 * G < NUB) MIX_PREFETCH_B(u + 2 * G);
.LBB0_510:
	s_mov_b32 s98, s12
	s_mov_b32 s99, s14
	s_mov_b32 s100, 1

; #define LAS __attribute__((address_space(3)))
; __device__ __forceinline__ unsigned pk2(float lo, float hi) { return f2bf(lo) | (f2bf(hi) << 16); }
; __device__ __forceinline__ void mix_phase(LAS unsigned char* lds, const Params& p, const int layer) {
;     ...
;             for (int i = 0; i < 2; ++i) {
;                 const int rl = (tid >> 5) + 16 * i, bi = prt ? rl + 15 : (rl >> 3) * 23 + 15 + (rl & 7), t = (r0 + rl) & 2047;
;                 const LAS float* sp = SL + bi * 264 + q * 8;
;                 const f32x4 u0 = *(const LAS f32x4*)sp, u1 = *(const LAS f32x4*)(sp + 4);
;                 f32x4 s0 = u0, s1 = u1;
; #pragma unroll 4
;                 for (int j = 1; j < w; ++j) { s0 += *(const LAS f32x4*)(sp - j * 264); s1 += *(const LAS f32x4*)(sp - j * 264 + 4); }
;                 const int cnt = (prt && t + 1 < w) ? t + 1 : w; const float inv = 1.0f / (float)cnt;
;                 const f32x4 d0 = s0 * inv - u0, d1 = s1 * inv - u1;
;                 v4u o; o.x = pk2(d0[0], d0[1]); o.y = pk2(d0[2], d0[3]); o.z = pk2(d1[0], d1[1]); o.w = pk2(d1[2], d1[3]);
;                 *(LAS v4u*)(At + rl * 264 + q * 8) = o;
;             }
.LBB0_585:
	v_cndmask_b32_e64 v0, v139, v140, s[52:53]
	v_mul_lo_u32 v0, v0, s19
	v_add_u32_e32 v86, v136, v0
	ds_read_b128 v[90:93], v86
	ds_read_b128 v[86:89], v86 offset:16
	s_lshl_b32 s13, 2, s12
	s_add_i32 s14, s13, -1
	s_cmp_gt_u32 s12, 1
	s_waitcnt lgkmcnt(0)
	v_mov_b64_e32 v[100:101], v[92:93]
	v_mov_b64_e32 v[96:97], v[88:89]
	s_mov_b32 s15, 1
	s_cselect_b64 s[48:49], -1, 0
	s_cmp_lt_u32 s12, 2
	v_mov_b64_e32 v[98:99], v[90:91]
	v_mov_b64_e32 v[94:95], v[86:87]
	v_add_u32_e32 v149, v120, v0
	v_add_u32_e32 v149, 0xfffff7c0, v149
	s_lshr_b32 s15, s14, 1
	s_cmp_eq_u32 s15, 0
	s_cbranch_scc1 .Lpw_tail_a
.Lpw_pair_a:
	ds_read_b128 v[150:153], v149 offset:1056
	ds_read_b128 v[154:157], v149 offset:1072
	ds_read_b128 v[158:161], v149
	ds_read_b128 v[252:255], v149 offset:16
	s_add_i32 s15, s15, -1
	v_add_u32_e32 v149, 0xfffff7c0, v149
	s_cmp_lg_u32 s15, 0
	s_waitcnt lgkmcnt(2)
	v_pk_add_f32 v[100:101], v[100:101], v[152:153]
	v_pk_add_f32 v[98:99], v[98:99], v[150:151]
	v_pk_add_f32 v[96:97], v[96:97], v[156:157]
	v_pk_add_f32 v[94:95], v[94:95], v[154:155]
	s_waitcnt lgkmcnt(0)
	v_pk_add_f32 v[100:101], v[100:101], v[160:161]
	v_pk_add_f32 v[98:99], v[98:99], v[158:159]
	v_pk_add_f32 v[96:97], v[96:97], v[254:255]
	v_pk_add_f32 v[94:95], v[94:95], v[252:253]
	s_cbranch_scc1 .Lpw_pair_a
.Lpw_tail_a:
	ds_read_b128 v[150:153], v149 offset:1056
	ds_read_b128 v[154:157], v149 offset:1072
	s_waitcnt lgkmcnt(0)
	v_pk_add_f32 v[100:101], v[100:101], v[152:153]
	v_pk_add_f32 v[98:99], v[98:99], v[150:151]
	v_pk_add_f32 v[96:97], v[96:97], v[156:157]
	v_pk_add_f32 v[94:95], v[94:95], v[154:155]
	v_add_u32_e32 v0, s7, v121
	v_and_b32_e32 v0, 0x7ff, v0
	v_add_u32_e32 v0, 1, v0
	v_min_u32_e32 v0, s13, v0
	v_mov_b32_e32 v149, s13
	v_cndmask_b32_e64 v0, v149, v0, s[52:53]
	v_cvt_f32_ubyte0_e32 v0, v0
	v_div_scale_f32 v149, s[16:17], v0, v0, 1.0
	v_rcp_f32_e32 v150, v149
	v_xor_b32_e32 v93, 0x80000000, v93
	v_xor_b32_e32 v92, 0x80000000, v92
	v_xor_b32_e32 v89, 0x80000000, v89
	v_fma_f32 v151, -v149, v150, 1.0
	v_fmac_f32_e32 v150, v151, v150
	v_div_scale_f32 v151, vcc, 1.0, v0, 1.0
	v_mul_f32_e32 v152, v151, v150
	v_fma_f32 v153, -v149, v152, v151
	v_fmac_f32_e32 v152, v153, v150
	v_fma_f32 v149, -v149, v152, v151
	v_div_fmas_f32 v149, v149, v150, v152
	v_div_fixup_f32 v0, v149, v0, 1.0
	v_pk_fma_f32 v[90:91], v[0:1], v[98:99], v[90:91] op_sel_hi:[0,1,1] neg_lo:[0,0,1] neg_hi:[0,0,1]
	v_xor_b32_e32 v88, 0x80000000, v88
	v_pk_fma_f32 v[92:93], v[0:1], v[100:101], v[92:93] op_sel_hi:[0,1,1]
	v_pk_fma_f32 v[96:97], v[0:1], v[96:97], v[88:89] op_sel_hi:[0,1,1]
	v_pk_fma_f32 v[88:89], v[0:1], v[94:95], v[86:87] op_sel_hi:[0,1,1] neg_lo:[0,0,1] neg_hi:[0,0,1]
	v_bfe_u32 v0, v90, 16, 1
	v_add3_u32 v0, v90, v0, s26
	v_bfe_u32 v86, v91, 16, 1
	v_lshrrev_b32_e32 v0, 16, v0
	v_add3_u32 v86, v91, v86, s26
	v_and_or_b32 v86, v86, s24, v0
	v_bfe_u32 v0, v92, 16, 1
	v_add3_u32 v0, v92, v0, s26
	v_bfe_u32 v87, v93, 16, 1
	v_lshrrev_b32_e32 v0, 16, v0
	v_add3_u32 v87, v93, v87, s26
	v_and_or_b32 v87, v87, s24, v0
	v_bfe_u32 v0, v88, 16, 1
	v_add3_u32 v0, v88, v0, s26
	v_bfe_u32 v88, v89, 16, 1
	v_lshrrev_b32_e32 v0, 16, v0
	v_add3_u32 v88, v89, v88, s26
	v_and_or_b32 v88, v88, s24, v0
	v_bfe_u32 v0, v96, 16, 1
	v_add3_u32 v0, v96, v0, s26
	v_bfe_u32 v89, v97, 16, 1
	v_lshrrev_b32_e32 v0, 16, v0
	v_add3_u32 v89, v97, v89, s26
	v_and_or_b32 v89, v89, s24, v0
	v_cndmask_b32_e64 v0, v114, v115, s[52:53]
	v_mul_lo_u32 v0, v0, s19
	ds_write_b128 v146, v[86:89]
	v_add_u32_e32 v86, v136, v0
	ds_read_b128 v[90:93], v86
	ds_read_b128 v[86:89], v86 offset:16
	s_mov_b32 s15, 1
	s_andn2_b64 vcc, exec, s[48:49]
	s_waitcnt lgkmcnt(0)
	v_mov_b64_e32 v[100:101], v[92:93]
	v_mov_b64_e32 v[96:97], v[88:89]
	v_mov_b64_e32 v[98:99], v[90:91]
	v_mov_b64_e32 v[94:95], v[86:87]
	v_add_u32_e32 v149, v120, v0
	v_add_u32_e32 v149, 0xfffff7c0, v149
	s_lshr_b32 s15, s14, 1
	s_cmp_eq_u32 s15, 0
	s_cbranch_scc1 .Lpw_tail_b

; #define LAS __attribute__((address_space(3)))
; __device__ __forceinline__ unsigned pk2(float lo, float hi) { return f2bf(lo) | (f2bf(hi) << 16); }
; __device__ __forceinline__ void mix_phase(LAS unsigned char* lds, const Params& p, const int layer) {
;     ...
;                 for (int j = 1; j < w; ++j) { s0 += *(const LAS f32x4*)(sp - j * 264); s1 += *(const LAS f32x4*)(sp - j * 264 + 4); }
;                 const int cnt = (prt && t + 1 < w) ? t + 1 : w; const float inv = 1.0f / (float)cnt;
;                 const f32x4 d0 = s0 * inv - u0, d1 = s1 * inv - u1;
;                 v4u o; o.x = pk2(d0[0], d0[1]); o.y = pk2(d0[2], d0[3]); o.z = pk2(d1[0], d1[1]); o.w = pk2(d1[2], d1[3]);
;                 *(LAS v4u*)(At + rl * 264 + q * 8) = o;
;             }
;             __syncthreads();
.Lpw_tail_b:
	ds_read_b128 v[150:153], v149 offset:1056
	ds_read_b128 v[154:157], v149 offset:1072
	s_waitcnt lgkmcnt(0)
	v_pk_add_f32 v[100:101], v[100:101], v[152:153]
	v_pk_add_f32 v[98:99], v[98:99], v[150:151]
	v_pk_add_f32 v[96:97], v[96:97], v[156:157]
	v_pk_add_f32 v[94:95], v[94:95], v[154:155]
	v_add_u32_e32 v0, s7, v131
	v_and_b32_e32 v0, 0x7ff, v0
	v_add_u32_e32 v0, 1, v0
	v_min_u32_e32 v0, s13, v0
	v_mov_b32_e32 v149, s13
	v_cndmask_b32_e64 v0, v149, v0, s[52:53]
	v_cvt_f32_ubyte0_e32 v0, v0
	v_div_scale_f32 v149, s[12:13], v0, v0, 1.0
	v_rcp_f32_e32 v150, v149
	v_xor_b32_e32 v93, 0x80000000, v93
	v_xor_b32_e32 v92, 0x80000000, v92
	v_xor_b32_e32 v89, 0x80000000, v89
	v_fma_f32 v151, -v149, v150, 1.0
	v_fmac_f32_e32 v150, v151, v150
	v_div_scale_f32 v151, vcc, 1.0, v0, 1.0
	v_mul_f32_e32 v152, v151, v150
	v_fma_f32 v153, -v149, v152, v151
	v_fmac_f32_e32 v152, v153, v150
	v_fma_f32 v149, -v149, v152, v151
	v_div_fmas_f32 v149, v149, v150, v152
	v_div_fixup_f32 v0, v149, v0, 1.0
	v_pk_fma_f32 v[90:91], v[0:1], v[98:99], v[90:91] op_sel_hi:[0,1,1] neg_lo:[0,0,1] neg_hi:[0,0,1]
	v_xor_b32_e32 v88, 0x80000000, v88
	v_pk_fma_f32 v[92:93], v[0:1], v[100:101], v[92:93] op_sel_hi:[0,1,1]
	v_pk_fma_f32 v[96:97], v[0:1], v[96:97], v[88:89] op_sel_hi:[0,1,1]
	v_pk_fma_f32 v[88:89], v[0:1], v[94:95], v[86:87] op_sel_hi:[0,1,1] neg_lo:[0,0,1] neg_hi:[0,0,1]
	v_bfe_u32 v0, v90, 16, 1
	v_add3_u32 v0, v90, v0, s26
	v_bfe_u32 v86, v91, 16, 1
	v_lshrrev_b32_e32 v0, 16, v0
	v_add3_u32 v86, v91, v86, s26
	v_and_or_b32 v86, v86, s24, v0
	v_bfe_u32 v0, v92, 16, 1
	v_add3_u32 v0, v92, v0, s26
	v_bfe_u32 v87, v93, 16, 1
	v_lshrrev_b32_e32 v0, 16, v0
	v_add3_u32 v87, v93, v87, s26
	v_and_or_b32 v87, v87, s24, v0
	v_bfe_u32 v0, v88, 16, 1
	v_add3_u32 v0, v88, v0, s26
	v_bfe_u32 v88, v89, 16, 1
	v_lshrrev_b32_e32 v0, 16, v0
	v_add3_u32 v88, v89, v88, s26
	v_and_or_b32 v88, v88, s24, v0
	v_bfe_u32 v0, v96, 16, 1
	v_add3_u32 v0, v96, v0, s26
	v_bfe_u32 v89, v97, 16, 1
	v_lshrrev_b32_e32 v0, 16, v0
	v_add3_u32 v89, v97, v89, s26
	v_and_or_b32 v89, v89, s24, v0
	ds_write_b128 v147, v[86:89]
	s_waitcnt lgkmcnt(0)
	s_barrier
; #define LAS __attribute__((address_space(3)))
; __device__ __forceinline__ unsigned pk2(float lo, float hi) { return f2bf(lo) | (f2bf(hi) << 16); }
; __device__ __forceinline__ float bflo(unsigned w) { return __uint_as_float(w << 16); }
; __device__ __forceinline__ float bfhi(unsigned w) { return __uint_as_float(w & 0xffff0000u); }
; __device__ __forceinline__ void mix_phase(LAS unsigned char* lds, const Params& p, const int layer) {
;     ...
;             for (int ks = 0; ks < 8; ++ks) {
;                 bf16x8 a[2];
; #pragma unroll
;                 for (int m = 0; m < 2; ++m) a[m] = *(const LAS bf16x8*)(At + (m * 16 + fr) * 264 + ks * 32 + fq * 8);
; #pragma unroll
;                 for (int m = 0; m < 2; ++m)
; #pragma unroll
;                     for (int n = 0; n < 2; ++n) acc[m][n] = __builtin_amdgcn_mfma_f32_16x16x32_bf16(b[n][ks], a[m], acc[m][n], 0, 0, 0);
;             }
;             bf16* YA = (bf16*)(ws + WS_YA);
; #pragma unroll
;             for (int m = 0; m < 2; ++m)
; #pragma unroll
;                 for (int n = 0; n < 2; ++n) { const int r = r0 + m * 16 + fr, ch = g * 256 + wid * 32 + n * 16 + fq * 4; const v2u sg = sgc[m][n];
;                     const f32x4 y = acc[m][n] * ps[n] * (f32x4){bflo(sg.x), bfhi(sg.x), bflo(sg.y), bfhi(sg.y)};
;                     v2u o; o.x = pk2(y[0], y[1]); o.y = pk2(y[2], y[3]); *(v2u*)(YA + (size_t)r * KCAT + ch) = o; }
	ds_read_b128 v[86:89], v148
	ds_read_b128 v[90:93], v148 offset:8448
	ds_read_b128 v[150:153], v148 offset:64
	ds_read_b128 v[154:157], v148 offset:8512
	s_waitcnt lgkmcnt(0)
	s_waitcnt vmcnt(15)
	v_mfma_f32_16x16x32_bf16 v[94:97], v[42:45], v[86:89], 0
	v_or_b32_e32 v0, s7, v135
	s_movk_i32 s12, 0x1800
	s_and_b64 vcc, exec, s[90:91]
	v_mfma_f32_16x16x32_bf16 v[86:89], v[74:77], v[86:89], 0
	v_mfma_f32_16x16x32_bf16 v[98:101], v[42:45], v[90:93], 0
	v_mfma_f32_16x16x32_bf16 v[90:93], v[74:77], v[90:93], 0
	v_mfma_f32_16x16x32_bf16 v[94:97], v[38:41], v[150:153], v[94:97]
	v_mfma_f32_16x16x32_bf16 v[86:89], v[70:73], v[150:153], v[86:89]
	v_mfma_f32_16x16x32_bf16 v[98:101], v[38:41], v[154:157], v[98:101]
	v_mfma_f32_16x16x32_bf16 v[90:93], v[70:73], v[154:157], v[90:93]
	ds_read_b128 v[150:153], v148 offset:128
	ds_read_b128 v[154:157], v148 offset:8576
	s_waitcnt lgkmcnt(1)
	v_mfma_f32_16x16x32_bf16 v[94:97], v[34:37], v[150:153], v[94:97]
	v_mfma_f32_16x16x32_bf16 v[86:89], v[66:69], v[150:153], v[86:89]
	s_waitcnt lgkmcnt(0)
	v_mfma_f32_16x16x32_bf16 v[98:101], v[34:37], v[154:157], v[98:101]
	v_mfma_f32_16x16x32_bf16 v[90:93], v[66:69], v[154:157], v[90:93]
	ds_read_b128 v[150:153], v148 offset:192
	ds_read_b128 v[154:157], v148 offset:8640
	s_waitcnt lgkmcnt(1)
	v_mfma_f32_16x16x32_bf16 v[94:97], v[30:33], v[150:153], v[94:97]
	s_waitcnt vmcnt(10)
	v_mfma_f32_16x16x32_bf16 v[86:89], v[62:65], v[150:153], v[86:89]
	s_waitcnt lgkmcnt(0)
	v_mfma_f32_16x16x32_bf16 v[98:101], v[30:33], v[154:157], v[98:101]
	v_mfma_f32_16x16x32_bf16 v[90:93], v[62:65], v[154:157], v[90:93]
	ds_read_b128 v[150:153], v148 offset:256
	ds_read_b128 v[154:157], v148 offset:8704
	s_waitcnt lgkmcnt(1)
	v_mfma_f32_16x16x32_bf16 v[94:97], v[26:29], v[150:153], v[94:97]
	v_mfma_f32_16x16x32_bf16 v[86:89], v[58:61], v[150:153], v[86:89]
	s_waitcnt lgkmcnt(0)
	v_mfma_f32_16x16x32_bf16 v[98:101], v[26:29], v[154:157], v[98:101]
	v_mfma_f32_16x16x32_bf16 v[90:93], v[58:61], v[154:157], v[90:93]
	ds_read_b128 v[150:153], v148 offset:320
	ds_read_b128 v[154:157], v148 offset:8768
	s_waitcnt lgkmcnt(1)
	v_mfma_f32_16x16x32_bf16 v[94:97], v[22:25], v[150:153], v[94:97]
	v_mfma_f32_16x16x32_bf16 v[86:89], v[54:57], v[150:153], v[86:89]
	s_waitcnt lgkmcnt(0)
	v_mfma_f32_16x16x32_bf16 v[98:101], v[22:25], v[154:157], v[98:101]
	v_mfma_f32_16x16x32_bf16 v[90:93], v[54:57], v[154:157], v[90:93]
	ds_read_b128 v[150:153], v148 offset:384
	ds_read_b128 v[154:157], v148 offset:8832
	s_waitcnt lgkmcnt(1)
	v_mfma_f32_16x16x32_bf16 v[94:97], v[18:21], v[150:153], v[94:97]
	v_mfma_f32_16x16x32_bf16 v[86:89], v[50:53], v[150:153], v[86:89]
	s_waitcnt lgkmcnt(0)
	v_mfma_f32_16x16x32_bf16 v[98:101], v[18:21], v[154:157], v[98:101]
	v_mfma_f32_16x16x32_bf16 v[90:93], v[50:53], v[154:157], v[90:93]
	ds_read_b128 v[150:153], v148 offset:448
	ds_read_b128 v[154:157], v148 offset:8896
	s_waitcnt lgkmcnt(1)
	v_mfma_f32_16x16x32_bf16 v[94:97], v[14:17], v[150:153], v[94:97]
	s_waitcnt lgkmcnt(0)
	v_mfma_f32_16x16x32_bf16 v[98:101], v[14:17], v[154:157], v[98:101]
	s_nop 5
	v_mul_f32_e64 v94, v82, v94
	v_mul_f32_e64 v95, v83, v95
	v_pk_mul_f32 v[96:97], v[84:85], v[96:97]
	v_mfma_f32_16x16x32_bf16 v[90:93], v[46:49], v[154:157], v[90:93]
	s_waitcnt vmcnt(7)
	v_lshlrev_b32_e32 v156, 16, v108
	v_and_b32_e32 v157, 0xffff0000, v108
	v_lshlrev_b32_e32 v108, 16, v109
	v_and_b32_e32 v109, 0xffff0000, v109
	v_pk_mul_f32 v[94:95], v[94:95], v[156:157]
	v_pk_mul_f32 v[96:97], v[96:97], v[108:109]
	v_bfe_u32 v108, v94, 16, 1
	v_add3_u32 v94, v94, v108, s26
	v_bfe_u32 v108, v95, 16, 1
	v_lshrrev_b32_e32 v94, 16, v94
	v_add3_u32 v95, v95, v108, s26
	v_and_or_b32 v94, v95, s24, v94
	v_bfe_u32 v95, v96, 16, 1
	v_mfma_f32_16x16x32_bf16 v[86:89], v[46:49], v[150:153], v[86:89]
	v_add_u32_e32 v150, s6, v137
	v_add3_u32 v95, v96, v95, s26
	v_bfe_u32 v96, v97, 16, 1
	v_mov_b64_e32 v[152:153], s[86:87]
	v_lshrrev_b32_e32 v95, 16, v95
	v_add3_u32 v96, v97, v96, s26
	v_ashrrev_i32_e32 v151, 31, v150
	v_mad_i64_i32 v[154:155], s[6:7], v0, s12, v[152:153]
	v_and_or_b32 v95, v96, s24, v95
	v_lshlrev_b64 v[96:97], 1, v[150:151]
	v_lshl_add_u64 v[108:109], v[154:155], 0, v[96:97]
	global_store_dwordx2 v[108:109], v[94:95], off
	v_pk_mul_f32 v[86:87], v[78:79], v[86:87]
	s_waitcnt vmcnt(5)
	v_lshlrev_b32_e32 v94, 16, v106
	v_and_b32_e32 v95, 0xffff0000, v106
	v_pk_mul_f32 v[86:87], v[86:87], v[94:95]
	v_pk_mul_f32 v[88:89], v[80:81], v[88:89]
	v_bfe_u32 v94, v86, 16, 1
	v_lshlrev_b32_e32 v106, 16, v107
	v_and_b32_e32 v107, 0xffff0000, v107
	v_add3_u32 v86, v86, v94, s26
	v_bfe_u32 v94, v87, 16, 1
	v_pk_mul_f32 v[88:89], v[88:89], v[106:107]
	v_lshrrev_b32_e32 v86, 16, v86
	v_add3_u32 v87, v87, v94, s26
	v_and_or_b32 v86, v87, s24, v86
	v_bfe_u32 v87, v88, 16, 1
	v_add3_u32 v87, v88, v87, s26
	v_bfe_u32 v88, v89, 16, 1
	v_lshrrev_b32_e32 v87, 16, v87
	v_add3_u32 v88, v89, v88, s26
	v_pk_mul_f32 v[94:95], v[82:83], v[98:99]
	v_lshlrev_b32_e32 v98, 16, v104
	v_and_b32_e32 v99, 0xffff0000, v104
	v_and_or_b32 v87, v88, s24, v87
	v_or_b32_e32 v0, 16, v0
	v_pk_mul_f32 v[94:95], v[94:95], v[98:99]
	global_store_dwordx2 v[108:109], v[86:87], off offset:32
	v_mad_i64_i32 v[86:87], s[6:7], v0, s12, v[152:153]
	v_bfe_u32 v0, v94, 16, 1
	v_pk_mul_f32 v[88:89], v[84:85], v[100:101]
	v_lshlrev_b32_e32 v100, 16, v105
	v_and_b32_e32 v101, 0xffff0000, v105
	v_add3_u32 v0, v94, v0, s26
	v_bfe_u32 v94, v95, 16, 1
	v_pk_mul_f32 v[88:89], v[88:89], v[100:101]
	v_lshrrev_b32_e32 v0, 16, v0
	v_add3_u32 v94, v95, v94, s26
	v_and_or_b32 v94, v94, s24, v0
	v_bfe_u32 v0, v88, 16, 1
	v_add3_u32 v0, v88, v0, s26
	v_bfe_u32 v88, v89, 16, 1
	v_lshrrev_b32_e32 v0, 16, v0
	v_add3_u32 v88, v89, v88, s26
	v_and_or_b32 v95, v88, s24, v0
	v_pk_mul_f32 v[88:89], v[80:81], v[92:93]
	v_pk_mul_f32 v[90:91], v[78:79], v[90:91]
	v_lshlrev_b32_e32 v92, 16, v102
	v_and_b32_e32 v93, 0xffff0000, v102
	v_pk_mul_f32 v[90:91], v[90:91], v[92:93]
	v_lshl_add_u64 v[86:87], v[86:87], 0, v[96:97]
	v_bfe_u32 v0, v90, 16, 1
	global_store_dwordx2 v[86:87], v[94:95], off
	v_lshlrev_b32_e32 v94, 16, v103
	v_and_b32_e32 v95, 0xffff0000, v103
	v_add3_u32 v0, v90, v0, s26
	v_bfe_u32 v90, v91, 16, 1
	v_pk_mul_f32 v[88:89], v[88:89], v[94:95]
	v_lshrrev_b32_e32 v0, 16, v0
	v_add3_u32 v90, v91, v90, s26
	v_and_or_b32 v90, v90, s24, v0
	v_bfe_u32 v0, v88, 16, 1
	v_add3_u32 v0, v88, v0, s26
	v_bfe_u32 v88, v89, 16, 1
	v_lshrrev_b32_e32 v0, 16, v0
	v_add3_u32 v88, v89, v88, s26
	v_readlane_b32 s6, v249, 62
	v_and_or_b32 v91, v88, s24, v0
	s_add_i32 s2, s2, s6
	s_waitcnt vmcnt(4)
	v_mov_b64_e32 v[102:103], v[126:127]
	v_mov_b64_e32 v[104:105], v[124:125]
	s_waitcnt vmcnt(3)
	v_mov_b64_e32 v[106:107], v[128:129]
	v_mov_b64_e32 v[108:109], v[122:123]
	global_store_dwordx2 v[86:87], v[90:91], off offset:32
	s_cbranch_vccz .LBB0_551

; __device__ __forceinline__ void ln_phase(const Params& p, const int layer, const int row_lo, const int row_hi, const int wg_id, const int n_wg) {
;     int tid_ = threadIdx.x; asm volatile("" : "+v"(tid_)); const int tid = tid_, lane = tid & 63, wave = tid >> 6;
;     const int gw = wg_id * NWAVES + wave, NGW = n_wg * NWAVES;
;     unsigned char* ws = p.ws; asm volatile("" : "+s"(ws)); float* Z = p.out; bf16* XB = (bf16*)(ws + WS_XB);
;     const float* g = p.in[19] + layer * DM; const float* bb = p.in[20] + layer * DM;
;     const bf16* OB = (const bf16*)(ws + WS_TMP);
;     for (int m0 = row_lo + gw; m0 < row_hi; m0 += 2 * NGW) {
;         const int m1r = m0 + NGW; const bool ok1 = m1r < row_hi; const int m1 = ok1 ? m1r : m0;
;         const v2u* ob0 = (const v2u*)(OB + (size_t)m0 * DM) + lane; const v2u* ob1 = (const v2u*)(OB + (size_t)m1 * DM) + lane;
;         f32x4 v0[8], v1[8]; v2u w0[8], w1[8]; float s0 = 0.f, s1 = 0.f;
;     ...
;         for (int j = 0; j < 8; ++j) { const f32x4 gv = *((const f32x4*)g + lane + 64 * j), bv = *((const f32x4*)bb + lane + 64 * j);
.LBB0_1024:
	s_add_i32 s0, s5, 6
	s_cmp_le_i32 s18, s0
	s_cselect_b64 s[8:9], -1, 0
	s_cmp_lt_i32 s0, s19
	s_cselect_b64 s[18:19], -1, 0
	s_and_b64 s[0:1], s[8:9], s[18:19]
	s_andn2_b64 vcc, exec, s[0:1]
	v_readlane_b32 s14, v248, 26
	v_readlane_b32 s15, v248, 27
	s_cbranch_vccnz .LBB0_1097
	v_mov_b32_e32 v0, v193
	v_readlane_b32 s36, v251, 1
	s_waitcnt vmcnt(1)
	v_ashrrev_i32_e32 v2, 6, v0
	v_readlane_b32 s2, v249, 37
	v_readlane_b32 s40, v251, 5
	v_readlane_b32 s41, v251, 6
	v_add_u32_e32 v66, s2, v2
	s_movk_i32 s2, 0x2400
	v_readlane_b32 s42, v251, 7
	v_readlane_b32 s43, v251, 8
	s_mov_b64 s[0:1], s[40:41]
	v_cmp_gt_i32_e32 vcc, s2, v66
	v_readlane_b32 s37, v251, 2
	v_readlane_b32 s38, v251, 3
	v_readlane_b32 s39, v251, 4
	s_and_saveexec_b64 s[42:43], vcc
	s_cbranch_execz .LBB0_1096
	v_and_b32_e32 v2, 63, v0
	s_add_u32 s2, s0, 0x21b04000
	v_lshlrev_b32_e32 v0, 3, v2
	s_addc_u32 s3, s1, 0
	v_lshl_add_u64 v[4:5], s[0:1], 0, v[0:1]
	s_mov_b64 s[0:1], 0x7b04000
	v_and_b32_e32 v3, 64, v223
	v_lshl_add_u64 v[70:71], v[4:5], 0, s[0:1]
	v_add_u32_e32 v3, 64, v3
	v_xor_b32_e32 v4, 1, v223
	v_cmp_lt_i32_e32 vcc, v4, v3
	s_lshl_b32 s6, s56, 11
	s_mov_b32 s7, s80
	v_cndmask_b32_e32 v4, v223, v4, vcc
	v_lshlrev_b32_e32 v142, 2, v4
	v_xor_b32_e32 v4, 2, v223
	v_cmp_lt_i32_e32 vcc, v4, v3
	s_lshl_b64 s[6:7], s[6:7], 2
	v_readlane_b32 s44, v251, 1
	v_cndmask_b32_e32 v4, v223, v4, vcc
	v_lshlrev_b32_e32 v143, 2, v4
	v_xor_b32_e32 v4, 4, v223
	v_cmp_lt_i32_e32 vcc, v4, v3
	v_readlane_b32 s45, v251, 2
	s_add_u32 s12, s44, s6
	v_cndmask_b32_e32 v4, v223, v4, vcc
	v_lshlrev_b32_e32 v144, 2, v4
	v_xor_b32_e32 v4, 8, v223
	v_cmp_lt_i32_e32 vcc, v4, v3
	v_readlane_b32 s68, v251, 9
	s_addc_u32 s13, s45, s7
	v_cndmask_b32_e32 v4, v223, v4, vcc
	v_lshlrev_b32_e32 v145, 2, v4
	v_xor_b32_e32 v4, 16, v223
	v_cmp_lt_i32_e32 vcc, v4, v3
	v_readlane_b32 s74, v251, 15
	v_readlane_b32 s75, v251, 16
	v_cndmask_b32_e32 v4, v223, v4, vcc
	v_lshlrev_b32_e32 v146, 2, v4
	v_xor_b32_e32 v4, 32, v223
	s_add_u32 s6, s74, s6
	v_cmp_lt_i32_e32 vcc, v4, v3
	s_addc_u32 s7, s75, s7
	v_mov_b32_e32 v5, v1
	v_cndmask_b32_e32 v3, v223, v4, vcc
	v_lshlrev_b32_e32 v4, 4, v2
	v_readlane_b32 s69, v251, 10
	v_readlane_b32 s70, v251, 11
	v_readlane_b32 s71, v251, 12
	v_readlane_b32 s72, v251, 13
	v_readlane_b32 s73, v251, 14
	v_lshl_add_u64 v[74:75], s[6:7], 0, v[4:5]
	v_lshl_add_u64 v[76:77], s[12:13], 0, v[4:5]
	s_mov_b64 s[0:1], 0x1000
	v_readlane_b32 s46, v251, 3
	v_readlane_b32 s47, v251, 4
	v_lshl_add_u64 v[78:79], v[74:75], 0, s[0:1]
	v_lshl_add_u64 v[80:81], v[76:77], 0, s[0:1]
	s_mov_b64 s[0:1], 0x1400
	v_ashrrev_i32_e32 v67, 31, v66
	v_readlane_b32 s60, v251, 21
	v_lshl_add_u64 v[72:73], s[46:47], 0, v[4:5]
	v_lshl_add_u64 v[82:83], v[74:75], 0, s[0:1]
	v_lshl_add_u64 v[84:85], v[76:77], 0, s[0:1]
	s_mov_b64 s[0:1], 0x1800
	v_lshlrev_b64 v[4:5], 12, v[66:67]
	v_readlane_b32 s72, v251, 33
	v_readlane_b32 s73, v251, 34
	v_lshl_add_u64 v[86:87], v[74:75], 0, s[0:1]
	v_lshl_add_u64 v[88:89], v[76:77], 0, s[0:1]
	s_mov_b64 s[0:1], 0x1c00
	v_or_b32_e32 v4, v4, v0
	v_readlane_b32 s61, v251, 22
	v_readlane_b32 s72, v248, 24
	v_lshl_add_u64 v[68:69], s[2:3], 0, v[0:1]
	v_lshlrev_b32_e32 v147, 2, v3
	v_lshl_add_u64 v[90:91], v[74:75], 0, s[0:1]
	v_lshl_add_u64 v[92:93], v[76:77], 0, s[0:1]
	v_lshlrev_b64 v[94:95], 13, v[66:67]
	v_lshl_add_u64 v[96:97], s[2:3], 0, v[4:5]
	s_mov_b64 s[44:45], 0
	v_lshlrev_b32_e32 v98, 4, v2
	v_mov_b64_e32 v[100:101], v[72:73]
	v_readlane_b32 s73, v248, 25
	s_mov_b64 s[46:47], s[60:61]
	v_readlane_b32 s48, v251, 5
	v_readlane_b32 s49, v251, 6
	v_readlane_b32 s50, v251, 7
	v_readlane_b32 s51, v251, 8
	v_readlane_b32 s62, v251, 23
	v_readlane_b32 s63, v251, 24
	v_readlane_b32 s64, v251, 25
	v_readlane_b32 s65, v251, 26
	v_readlane_b32 s66, v251, 27
	v_readlane_b32 s67, v251, 28
	v_readlane_b32 s68, v251, 29
	v_readlane_b32 s69, v251, 30
	v_readlane_b32 s70, v251, 31
	v_readlane_b32 s71, v251, 32
	v_readlane_b32 s74, v251, 35
	v_readlane_b32 s75, v251, 36
	global_load_dwordx4 v[152:155], v[74:75], off
	global_load_dwordx4 v[156:159], v[76:77], off
	global_load_dwordx4 v[160:163], v[74:75], off offset:1024
	global_load_dwordx4 v[168:171], v[76:77], off offset:1024
	global_load_dwordx4 v[172:175], v[74:75], off offset:2048
	global_load_dwordx4 v[176:179], v[76:77], off offset:2048
	global_load_dwordx4 v[180:183], v[74:75], off offset:3072
	global_load_dwordx4 v[184:187], v[76:77], off offset:3072
	global_load_dwordx4 v[188:191], v[78:79], off
	global_load_dwordx4 v[196:199], v[80:81], off
	global_load_dwordx4 v[210:213], v[82:83], off
	global_load_dwordx4 v[224:227], v[84:85], off
	global_load_dwordx4 v[228:231], v[86:87], off
	global_load_dwordx4 v[232:235], v[88:89], off
	global_load_dwordx4 v[236:239], v[90:91], off
	global_load_dwordx4 v[244:247], v[92:93], off
	s_branch .LBB0_1029

; __device__ __forceinline__ float bflo(unsigned w) { return __uint_as_float(w << 16); }
; __device__ __forceinline__ float bfhi(unsigned w) { return __uint_as_float(w & 0xffff0000u); }
; __device__ __forceinline__ void ln_phase(const Params& p, const int layer, const int row_lo, const int row_hi, const int wg_id, const int n_wg) {
;     ...
;         const v2u* ob0 = (const v2u*)(OB + (size_t)m0 * DM) + lane; const v2u* ob1 = (const v2u*)(OB + (size_t)m1 * DM) + lane;
;         f32x4 v0[8], v1[8]; v2u w0[8], w1[8]; float s0 = 0.f, s1 = 0.f;
;         if (layer == 0) {
;             const f32x4* xr0 = (const f32x4*)((m0 < NP) ? p.in[0] + (size_t)m0 * DM : p.in[1] + (size_t)(m0 - NP) * DM) + lane;
;             const f32x4* xr1 = (const f32x4*)((m1 < NP) ? p.in[0] + (size_t)m1 * DM : p.in[1] + (size_t)(m1 - NP) * DM) + lane;
; #pragma unroll
;             for (int j = 0; j < 8; ++j) { v0[j] = xr0[64 * j]; v1[j] = xr1[64 * j]; w0[j] = ob0[64 * j]; w1[j] = ob1[64 * j]; }
;         } else {
;             const v2u* xb0 = (const v2u*)(XB + (size_t)m0 * DM) + lane; const v2u* xb1 = (const v2u*)(XB + (size_t)m1 * DM) + lane;
;             v2u a0[8], a1[8];
; #pragma unroll
;             for (int j = 0; j < 8; ++j) { a0[j] = xb0[64 * j]; a1[j] = xb1[64 * j]; w0[j] = ob0[64 * j]; w1[j] = ob1[64 * j]; }
; #pragma unroll
;             for (int j = 0; j < 8; ++j) { v0[j] = (f32x4){bflo(a0[j].x), bfhi(a0[j].x), bflo(a0[j].y), bfhi(a0[j].y)}; v1[j] = (f32x4){bflo(a1[j].x), bfhi(a1[j].x), bflo(a1[j].y), bfhi(a1[j].y)}; }
;         }
; #pragma unroll
;         for (int j = 0; j < 8; ++j) { v0[j] = v0[j] * DN_ALPHA + (f32x4){bflo(w0[j].x), bfhi(w0[j].x), bflo(w0[j].y), bfhi(w0[j].y)};
;             v1[j] = v1[j] * DN_ALPHA + (f32x4){bflo(w1[j].x), bfhi(w1[j].x), bflo(w1[j].y), bfhi(w1[j].y)};
;             s0 += (v0[j].x + v0[j].y) + (v0[j].z + v0[j].w); s1 += (v1[j].x + v1[j].y) + (v1[j].z + v1[j].w); }
.LBB0_1033:
	v_lshlrev_b64 v[104:105], 1, v[102:103]
	v_lshl_add_u64 v[110:111], v[68:69], 0, v[104:105]
	global_load_dwordx2 v[118:119], v[96:97], off offset:3584
	global_load_dwordx2 v[120:121], v[96:97], off offset:3072
	global_load_dwordx2 v[122:123], v[96:97], off offset:2560
	global_load_dwordx2 v[126:127], v[96:97], off offset:2048
	global_load_dwordx2 v[130:131], v[96:97], off offset:1536
	global_load_dwordx2 v[106:107], v[96:97], off offset:1024
	global_load_dwordx2 v[138:139], v[96:97], off offset:512
	global_load_dwordx2 v[112:113], v[96:97], off
	global_load_dwordx2 v[140:141], v[110:111], off
	global_load_dwordx2 v[148:149], v[110:111], off offset:512
	global_load_dwordx2 v[108:109], v[110:111], off offset:1024
	global_load_dwordx2 v[136:137], v[110:111], off offset:1536
	global_load_dwordx2 v[134:135], v[110:111], off offset:2048
	global_load_dwordx2 v[132:133], v[110:111], off offset:2560
	global_load_dwordx2 v[128:129], v[110:111], off offset:3072
	global_load_dwordx2 v[124:125], v[110:111], off offset:3584
	s_mov_b32 s2, 0xf800000
	v_lshl_add_u64 v[102:103], v[102:103], 2, v[72:73]
	s_waitcnt lgkmcnt(0)
	s_waitcnt vmcnt(8)
	v_lshlrev_b32_e32 v110, 16, v112
	v_and_b32_e32 v111, 0xffff0000, v112
	v_lshlrev_b32_e32 v112, 16, v113
	v_and_b32_e32 v113, 0xffff0000, v113
	v_pk_fma_f32 v[114:115], v[64:65], s[4:5], v[112:113] op_sel_hi:[1,0,1]
	v_pk_fma_f32 v[116:117], v[62:63], s[4:5], v[110:111] op_sel_hi:[1,0,1]
	s_waitcnt vmcnt(7)
	v_lshlrev_b32_e32 v62, 16, v140
	v_and_b32_e32 v63, 0xffff0000, v140
	v_lshlrev_b32_e32 v64, 16, v141
	v_and_b32_e32 v65, 0xffff0000, v141
	v_pk_fma_f32 v[110:111], v[60:61], s[4:5], v[64:65] op_sel_hi:[1,0,1]
	v_pk_fma_f32 v[112:113], v[58:59], s[4:5], v[62:63] op_sel_hi:[1,0,1]
	v_lshlrev_b32_e32 v58, 16, v138
	v_and_b32_e32 v59, 0xffff0000, v138
	v_lshlrev_b32_e32 v60, 16, v139
	v_and_b32_e32 v61, 0xffff0000, v139
	v_pk_fma_f32 v[56:57], v[56:57], s[4:5], v[60:61] op_sel_hi:[1,0,1]
	v_pk_fma_f32 v[54:55], v[54:55], s[4:5], v[58:59] op_sel_hi:[1,0,1]
	s_waitcnt vmcnt(6)
	v_lshlrev_b32_e32 v58, 16, v148
	v_and_b32_e32 v59, 0xffff0000, v148
	v_lshlrev_b32_e32 v60, 16, v149
	v_and_b32_e32 v61, 0xffff0000, v149
	v_pk_fma_f32 v[52:53], v[52:53], s[4:5], v[60:61] op_sel_hi:[1,0,1]
	v_pk_fma_f32 v[50:51], v[50:51], s[4:5], v[58:59] op_sel_hi:[1,0,1]
	v_mov_b32_e32 v58, v54
	v_mov_b32_e32 v59, v116
	v_mov_b32_e32 v60, v55
	v_mov_b32_e32 v61, v117
	v_pk_add_f32 v[58:59], v[58:59], v[60:61]
	v_mov_b32_e32 v60, v57
	v_mov_b32_e32 v61, v115
	v_mov_b32_e32 v62, v56
	v_mov_b32_e32 v63, v114
	v_pk_add_f32 v[60:61], v[60:61], v[62:63]
	v_mov_b32_e32 v62, v111
	v_pk_add_f32 v[58:59], v[58:59], v[60:61]
	v_mov_b32_e32 v60, v113
	v_add_f32_e32 v0, 0, v59
	v_add_f32_e32 v139, v58, v0
	v_mov_b32_e32 v58, v112
	v_mov_b32_e32 v59, v50
	v_mov_b32_e32 v61, v51
	v_pk_add_f32 v[58:59], v[58:59], v[60:61]
	v_mov_b32_e32 v60, v110
	v_mov_b32_e32 v61, v52
	v_mov_b32_e32 v63, v53
	v_pk_add_f32 v[60:61], v[60:61], v[62:63]
	s_nop 0
	v_pk_add_f32 v[58:59], v[58:59], v[60:61]
	v_lshlrev_b32_e32 v60, 16, v107
	v_add_f32_e32 v0, 0, v58
	v_add_f32_e32 v140, v0, v59
	v_lshlrev_b32_e32 v58, 16, v106
	v_and_b32_e32 v59, 0xffff0000, v106
	v_and_b32_e32 v61, 0xffff0000, v107
	v_pk_fma_f32 v[46:47], v[46:47], s[4:5], v[58:59] op_sel_hi:[1,0,1]
	v_pk_fma_f32 v[48:49], v[48:49], s[4:5], v[60:61] op_sel_hi:[1,0,1]
	s_waitcnt vmcnt(5)
	v_lshlrev_b32_e32 v58, 16, v108
	v_and_b32_e32 v59, 0xffff0000, v108
	v_lshlrev_b32_e32 v60, 16, v109
	v_and_b32_e32 v61, 0xffff0000, v109
	v_pk_fma_f32 v[108:109], v[44:45], s[4:5], v[60:61] op_sel_hi:[1,0,1]
	v_pk_fma_f32 v[106:107], v[42:43], s[4:5], v[58:59] op_sel_hi:[1,0,1]
	v_mov_b32_e32 v42, v46
	v_mov_b32_e32 v43, v49
	v_pk_mov_b32 v[44:45], v[46:47], v[48:49] op_sel:[1,0]
	s_nop 0
	v_pk_add_f32 v[42:43], v[42:43], v[44:45]
	v_mov_b32_e32 v44, v106
	v_pk_add_f32 v[148:149], v[42:43], v[42:43] op_sel_hi:[0,1]
	v_pk_mov_b32 v[42:43], v[106:107], v[108:109] op_sel:[1,0]
	v_mov_b32_e32 v45, v109
	v_pk_add_f32 v[42:43], v[42:43], v[44:45]
	v_lshlrev_b32_e32 v44, 16, v131
	v_pk_add_f32 v[150:151], v[42:43], v[42:43] op_sel:[0,1] op_sel_hi:[1,0]
	v_lshlrev_b32_e32 v42, 16, v130
	v_and_b32_e32 v43, 0xffff0000, v130
	v_and_b32_e32 v45, 0xffff0000, v131
	v_pk_fma_f32 v[64:65], v[28:29], s[4:5], v[44:45] op_sel_hi:[1,0,1]
	v_pk_fma_f32 v[62:63], v[26:27], s[4:5], v[42:43] op_sel_hi:[1,0,1]
	v_lshlrev_b32_e32 v42, 16, v126
	v_and_b32_e32 v43, 0xffff0000, v126
	v_lshlrev_b32_e32 v44, 16, v127
	v_and_b32_e32 v45, 0xffff0000, v127
	s_waitcnt vmcnt(4)
	v_lshlrev_b32_e32 v26, 16, v136
	v_and_b32_e32 v27, 0xffff0000, v136
	v_lshlrev_b32_e32 v28, 16, v137
	v_and_b32_e32 v29, 0xffff0000, v137
	v_pk_fma_f32 v[44:45], v[36:37], s[4:5], v[44:45] op_sel_hi:[1,0,1]
	v_pk_fma_f32 v[42:43], v[34:35], s[4:5], v[42:43] op_sel_hi:[1,0,1]
	v_pk_fma_f32 v[60:61], v[24:25], s[4:5], v[28:29] op_sel_hi:[1,0,1]
	v_pk_fma_f32 v[58:59], v[22:23], s[4:5], v[26:27] op_sel_hi:[1,0,1]
	v_add_f32_e32 v23, v62, v63
	v_add_f32_e32 v25, v65, v64
	s_waitcnt vmcnt(3)
; __device__ __forceinline__ float bflo(unsigned w) { return __uint_as_float(w << 16); }
; __device__ __forceinline__ float bfhi(unsigned w) { return __uint_as_float(w & 0xffff0000u); }
; __device__ __forceinline__ void ln_phase(const Params& p, const int layer, const int row_lo, const int row_hi, const int wg_id, const int n_wg) {
;     ...
;         for (int j = 0; j < 8; ++j) { v0[j] = v0[j] * DN_ALPHA + (f32x4){bflo(w0[j].x), bfhi(w0[j].x), bflo(w0[j].y), bfhi(w0[j].y)};
;             v1[j] = v1[j] * DN_ALPHA + (f32x4){bflo(w1[j].x), bfhi(w1[j].x), bflo(w1[j].y), bfhi(w1[j].y)};
;             s0 += (v0[j].x + v0[j].y) + (v0[j].z + v0[j].w); s1 += (v1[j].x + v1[j].y) + (v1[j].z + v1[j].w); }
;         const float mean0 = wave_sum(s0) * (1.f / DM), mean1 = wave_sum(s1) * (1.f / DM); float q0 = 0.f, q1 = 0.f;
; #pragma unroll
;         for (int j = 0; j < 8; ++j) { v0[j] = v0[j] - mean0; v1[j] = v1[j] - mean1;
;             q0 += (v0[j].x * v0[j].x + v0[j].y * v0[j].y) + (v0[j].z * v0[j].z + v0[j].w * v0[j].w); q1 += (v1[j].x * v1[j].x + v1[j].y * v1[j].y) + (v1[j].z * v1[j].z + v1[j].w * v1[j].w); }
	v_lshlrev_b32_e32 v34, 16, v134
	v_and_b32_e32 v35, 0xffff0000, v134
	v_lshlrev_b32_e32 v36, 16, v135
	v_and_b32_e32 v37, 0xffff0000, v135
	v_mov_b32_e32 v22, v42
	v_mov_b32_e32 v24, v43
	v_mov_b32_e32 v148, v45
	v_mov_b32_e32 v138, v44
	v_pk_fma_f32 v[40:41], v[40:41], s[4:5], v[36:37] op_sel_hi:[1,0,1]
	v_pk_fma_f32 v[38:39], v[38:39], s[4:5], v[34:35] op_sel_hi:[1,0,1]
	v_pk_add_f32 v[22:23], v[22:23], v[24:25]
	v_pk_add_f32 v[24:25], v[148:149], v[138:139]
	v_add_f32_e32 v26, v58, v59
	v_add_f32_e32 v28, v60, v61
	v_pk_add_f32 v[22:23], v[22:23], v[24:25]
	v_mov_b32_e32 v141, v38
	v_mov_b32_e32 v151, v39
	v_mov_b32_e32 v27, v40
	v_mov_b32_e32 v29, v41
	v_pk_add_f32 v[126:127], v[22:23], v[22:23] op_sel_hi:[0,1]
	v_pk_add_f32 v[22:23], v[140:141], v[150:151]
	v_pk_add_f32 v[24:25], v[26:27], v[28:29]
	s_nop 0
	v_pk_add_f32 v[22:23], v[22:23], v[24:25]
	v_lshlrev_b32_e32 v24, 16, v123
	v_pk_add_f32 v[130:131], v[22:23], v[22:23] op_sel:[0,1] op_sel_hi:[1,0]
	v_lshlrev_b32_e32 v22, 16, v122
	v_and_b32_e32 v23, 0xffff0000, v122
	v_and_b32_e32 v25, 0xffff0000, v123
	v_pk_fma_f32 v[34:35], v[14:15], s[4:5], v[22:23] op_sel_hi:[1,0,1]
	v_pk_fma_f32 v[36:37], v[16:17], s[4:5], v[24:25] op_sel_hi:[1,0,1]
	s_waitcnt vmcnt(2)
	v_lshlrev_b32_e32 v14, 16, v132
	v_and_b32_e32 v15, 0xffff0000, v132
	v_lshlrev_b32_e32 v16, 16, v133
	v_and_b32_e32 v17, 0xffff0000, v133
	v_pk_fma_f32 v[32:33], v[32:33], s[4:5], v[16:17] op_sel_hi:[1,0,1]
	v_pk_fma_f32 v[30:31], v[30:31], s[4:5], v[14:15] op_sel_hi:[1,0,1]
	v_mov_b32_e32 v14, v34
	v_mov_b32_e32 v15, v37
	v_pk_mov_b32 v[16:17], v[34:35], v[36:37] op_sel:[1,0]
	s_nop 0
	v_pk_add_f32 v[14:15], v[14:15], v[16:17]
	v_mov_b32_e32 v16, v30
	v_pk_add_f32 v[122:123], v[14:15], v[14:15] op_sel_hi:[0,1]
	v_pk_mov_b32 v[14:15], v[30:31], v[32:33] op_sel:[1,0]
	v_mov_b32_e32 v17, v33
	v_pk_add_f32 v[14:15], v[14:15], v[16:17]
	v_lshlrev_b32_e32 v16, 16, v121
	v_pk_add_f32 v[132:133], v[14:15], v[14:15] op_sel:[0,1] op_sel_hi:[1,0]
	v_lshlrev_b32_e32 v14, 16, v120
	v_and_b32_e32 v15, 0xffff0000, v120
	v_and_b32_e32 v17, 0xffff0000, v121
	v_pk_fma_f32 v[28:29], v[8:9], s[4:5], v[16:17] op_sel_hi:[1,0,1]
	v_pk_fma_f32 v[26:27], v[6:7], s[4:5], v[14:15] op_sel_hi:[1,0,1]
	s_waitcnt vmcnt(1)
	v_lshlrev_b32_e32 v8, 16, v129
	v_and_b32_e32 v9, 0xffff0000, v129
	v_lshlrev_b32_e32 v16, 16, v118
	v_and_b32_e32 v17, 0xffff0000, v118
	v_lshlrev_b32_e32 v14, 16, v119
	v_and_b32_e32 v15, 0xffff0000, v119
	v_lshlrev_b32_e32 v6, 16, v128
	v_and_b32_e32 v7, 0xffff0000, v128
	v_pk_fma_f32 v[24:25], v[20:21], s[4:5], v[8:9] op_sel_hi:[1,0,1]
	v_pk_fma_f32 v[14:15], v[4:5], s[4:5], v[14:15] op_sel_hi:[1,0,1]
	v_pk_fma_f32 v[20:21], v[2:3], s[4:5], v[16:17] op_sel_hi:[1,0,1]
	v_pk_fma_f32 v[22:23], v[18:19], s[4:5], v[6:7] op_sel_hi:[1,0,1]
	v_add_f32_e32 v7, v26, v27
	v_add_f32_e32 v9, v29, v28
	s_waitcnt vmcnt(0)
	v_lshlrev_b32_e32 v2, 16, v124
	v_and_b32_e32 v3, 0xffff0000, v124
	v_lshlrev_b32_e32 v4, 16, v125
	v_and_b32_e32 v5, 0xffff0000, v125
	v_mov_b32_e32 v6, v20
	v_mov_b32_e32 v8, v21
	v_mov_b32_e32 v122, v15
	v_mov_b32_e32 v126, v14
	v_pk_fma_f32 v[16:17], v[12:13], s[4:5], v[4:5] op_sel_hi:[1,0,1]
	v_pk_fma_f32 v[18:19], v[10:11], s[4:5], v[2:3] op_sel_hi:[1,0,1]
	v_pk_add_f32 v[2:3], v[6:7], v[8:9]
	v_pk_add_f32 v[4:5], v[122:123], v[126:127]
	v_add_f32_e32 v120, v22, v23
	v_add_f32_e32 v128, v24, v25
	v_pk_add_f32 v[2:3], v[2:3], v[4:5]
	v_mov_b32_e32 v131, v18
	v_mov_b32_e32 v133, v19
	v_mov_b32_e32 v121, v16
	v_mov_b32_e32 v129, v17
	v_add_f32_e32 v0, v2, v3
	v_pk_add_f32 v[2:3], v[130:131], v[132:133]
	v_pk_add_f32 v[4:5], v[120:121], v[128:129]
	s_nop 0
	v_pk_add_f32 v[2:3], v[2:3], v[4:5]
	s_nop 0
	v_add_f32_e32 v2, v2, v3
	ds_bpermute_b32 v3, v142, v0
	s_waitcnt lgkmcnt(0)
	v_add_f32_e32 v0, v0, v3
	ds_bpermute_b32 v3, v143, v0
	s_waitcnt lgkmcnt(0)
	v_add_f32_e32 v0, v0, v3
	ds_bpermute_b32 v3, v144, v0
	s_waitcnt lgkmcnt(0)
	v_add_f32_e32 v0, v0, v3
	ds_bpermute_b32 v3, v145, v0
	s_waitcnt lgkmcnt(0)
	v_add_f32_e32 v0, v0, v3
	ds_bpermute_b32 v3, v146, v0
	s_waitcnt lgkmcnt(0)
	v_add_f32_e32 v0, v0, v3
	ds_bpermute_b32 v3, v147, v0
	s_waitcnt lgkmcnt(0)
	v_add_f32_e32 v67, v0, v3
	ds_bpermute_b32 v0, v142, v2
	v_fmamk_f32 v117, v67, 0xba000000, v117
	v_fmac_f32_e32 v116, 0xba000000, v67
	v_fmamk_f32 v119, v67, 0xba000000, v55
	v_fmac_f32_e32 v54, 0xba000000, v67
	s_waitcnt lgkmcnt(0)
	v_add_f32_e32 v0, v2, v0
	ds_bpermute_b32 v2, v143, v0
	v_mov_b32_e32 v118, v117
	v_fmac_f32_e32 v114, 0xba000000, v67
	v_fmac_f32_e32 v56, 0xba000000, v67
	v_mov_b32_e32 v3, v54
	s_waitcnt lgkmcnt(0)
	v_add_f32_e32 v0, v0, v2
	ds_bpermute_b32 v2, v144, v0
	v_pk_mul_f32 v[4:5], v[118:119], v[118:119]
	v_fmamk_f32 v115, v67, 0xba000000, v115
	v_fmamk_f32 v127, v67, 0xba000000, v57
	v_mov_b32_e32 v126, v115
	s_waitcnt lgkmcnt(0)
	v_add_f32_e32 v0, v0, v2
	ds_bpermute_b32 v2, v145, v0
	v_fmamk_f32 v49, v67, 0xba000000, v49
	v_fmac_f32_e32 v48, 0xba000000, v67
	v_fmamk_f32 v47, v67, 0xba000000, v47
	v_fmac_f32_e32 v46, 0xba000000, v67
	s_waitcnt lgkmcnt(0)
	v_add_f32_e32 v0, v0, v2
	ds_bpermute_b32 v2, v146, v0
	v_fmac_f32_e32 v62, 0xba000000, v67
	v_fmac_f32_e32 v64, 0xba000000, v67
	v_fmamk_f32 v63, v67, 0xba000000, v63
	v_fmamk_f32 v65, v67, 0xba000000, v65
	s_waitcnt lgkmcnt(0)
	v_add_f32_e32 v0, v0, v2
	ds_bpermute_b32 v2, v147, v0
	v_fmamk_f32 v45, v67, 0xba000000, v45
	v_fmac_f32_e32 v44, 0xba000000, v67
	v_fmamk_f32 v43, v67, 0xba000000, v43
	v_fmac_f32_e32 v42, 0xba000000, v67
	s_waitcnt lgkmcnt(0)
; __device__ __forceinline__ void ln_phase(const Params& p, const int layer, const int row_lo, const int row_hi, const int wg_id, const int n_wg) {
;     ...
;         const float mean0 = wave_sum(s0) * (1.f / DM), mean1 = wave_sum(s1) * (1.f / DM); float q0 = 0.f, q1 = 0.f;
; #pragma unroll
;         for (int j = 0; j < 8; ++j) { v0[j] = v0[j] - mean0; v1[j] = v1[j] - mean1;
;             q0 += (v0[j].x * v0[j].x + v0[j].y * v0[j].y) + (v0[j].z * v0[j].z + v0[j].w * v0[j].w); q1 += (v1[j].x * v1[j].x + v1[j].y * v1[j].y) + (v1[j].z * v1[j].z + v1[j].w * v1[j].w); }
;         const float rstd0 = 1.f / sqrtf(wave_sum(q0) * (1.f / DM) + LN_EPS), rstd1 = 1.f / sqrtf(wave_sum(q1) * (1.f / DM) + LN_EPS);
	v_add_f32_e32 v99, v0, v2
	v_mov_b32_e32 v2, v116
	v_pk_fma_f32 v[2:3], v[2:3], v[2:3], v[4:5]
	v_mov_b32_e32 v4, v114
	v_mov_b32_e32 v5, v56
	v_fmamk_f32 v113, v99, 0xba000000, v113
	v_pk_mul_f32 v[4:5], v[4:5], v[4:5]
	v_fmamk_f32 v111, v99, 0xba000000, v111
	v_fmac_f32_e32 v112, 0xba000000, v99
	v_fmamk_f32 v123, v99, 0xba000000, v51
	v_fmac_f32_e32 v50, 0xba000000, v99
	v_pk_fma_f32 v[4:5], v[126:127], v[126:127], v[4:5]
	v_mov_b32_e32 v122, v113
	v_fmac_f32_e32 v110, 0xba000000, v99
	v_fmamk_f32 v125, v99, 0xba000000, v53
	v_fmac_f32_e32 v52, 0xba000000, v99
	v_pk_add_f32 v[2:3], v[2:3], v[4:5]
	v_mov_b32_e32 v4, v112
	v_mov_b32_e32 v5, v50
	v_pk_mul_f32 v[6:7], v[122:123], v[122:123]
	v_mov_b32_e32 v124, v111
	v_pk_fma_f32 v[4:5], v[4:5], v[4:5], v[6:7]
	v_mov_b32_e32 v6, v110
	v_mov_b32_e32 v7, v52
	v_pk_mul_f32 v[8:9], v[124:125], v[124:125]
	v_fmamk_f32 v109, v99, 0xba000000, v109
	v_pk_fma_f32 v[6:7], v[6:7], v[6:7], v[8:9]
	v_pk_mul_f32 v[8:9], v[46:47], v[46:47]
	v_pk_add_f32 v[4:5], v[4:5], v[6:7]
	v_pk_mul_f32 v[6:7], v[48:49], v[48:49]
	v_fmac_f32_e32 v108, 0xba000000, v99
	v_fmamk_f32 v107, v99, 0xba000000, v107
	v_fmac_f32_e32 v106, 0xba000000, v99
	v_pk_mov_b32 v[10:11], v[8:9], v[6:7] op_sel:[1,0]
	v_mov_b32_e32 v9, v7
	v_pk_add_f32 v[6:7], v[8:9], v[10:11]
	v_pk_mul_f32 v[8:9], v[108:109], v[108:109]
	v_pk_mul_f32 v[10:11], v[106:107], v[106:107]
	v_mul_f32_e32 v0, v62, v62
	v_pk_mov_b32 v[12:13], v[10:11], v[8:9] op_sel:[1,0]
	v_mov_b32_e32 v11, v9
	v_pk_add_f32 v[8:9], v[12:13], v[10:11]
	v_fmac_f32_e32 v58, 0xba000000, v99
	v_pk_fma_f32 v[10:11], v[62:63], v[62:63], v[0:1] op_sel_hi:[1,1,0]
	v_mul_f32_e32 v0, v64, v64
	v_fmac_f32_e32 v60, 0xba000000, v99
	v_fmamk_f32 v59, v99, 0xba000000, v59
	v_pk_fma_f32 v[12:13], v[64:65], v[64:65], v[0:1] op_sel_hi:[1,1,0]
	v_mul_f32_e32 v0, v58, v58
	v_fmamk_f32 v61, v99, 0xba000000, v61
	v_pk_fma_f32 v[120:121], v[58:59], v[58:59], v[0:1] op_sel_hi:[1,1,0]
	v_mul_f32_e32 v0, v60, v60
	v_pk_add_f32 v[2:3], v[2:3], v[2:3] op_sel_hi:[0,1]
	v_pk_add_f32 v[4:5], v[4:5], v[4:5] op_sel_hi:[0,1]
	v_pk_add_f32 v[6:7], v[6:7], v[6:7] op_sel_hi:[0,1]
	v_pk_add_f32 v[8:9], v[8:9], v[8:9] op_sel_hi:[0,1]
	v_pk_fma_f32 v[128:129], v[60:61], v[60:61], v[0:1] op_sel_hi:[1,1,0]
	v_fmamk_f32 v41, v99, 0xba000000, v41
	v_fmac_f32_e32 v40, 0xba000000, v99
	v_fmamk_f32 v39, v99, 0xba000000, v39
	v_fmac_f32_e32 v38, 0xba000000, v99
	v_mul_f32_e32 v2, v44, v44
	v_mul_f32_e32 v6, v45, v45
	v_mul_f32_e32 v120, v38, v38
	v_mul_f32_e32 v128, v39, v39
	v_mul_f32_e32 v8, v40, v40
	v_mul_f32_e32 v4, v41, v41
	v_mul_f32_e32 v10, v42, v42
	v_mul_f32_e32 v12, v43, v43
	v_pk_add_f32 v[2:3], v[6:7], v[2:3]
	v_pk_add_f32 v[6:7], v[120:121], v[128:129]
	v_pk_add_f32 v[4:5], v[8:9], v[4:5]
	v_fmamk_f32 v37, v67, 0xba000000, v37
	v_fmac_f32_e32 v36, 0xba000000, v67
	v_fmamk_f32 v35, v67, 0xba000000, v35
	v_fmac_f32_e32 v34, 0xba000000, v67
	v_pk_add_f32 v[10:11], v[10:11], v[12:13]
	v_pk_add_f32 v[4:5], v[6:7], v[4:5]
	v_pk_mul_f32 v[6:7], v[36:37], v[36:37]
	v_pk_mul_f32 v[8:9], v[34:35], v[34:35]
	v_pk_add_f32 v[2:3], v[10:11], v[2:3]
	v_fmamk_f32 v33, v99, 0xba000000, v33
	v_fmac_f32_e32 v32, 0xba000000, v99
	v_fmamk_f32 v31, v99, 0xba000000, v31
	v_fmac_f32_e32 v30, 0xba000000, v99
	v_pk_mov_b32 v[10:11], v[8:9], v[6:7] op_sel:[1,0]
	v_mov_b32_e32 v9, v7
	v_pk_add_f32 v[6:7], v[8:9], v[10:11]
	v_pk_mul_f32 v[8:9], v[32:33], v[32:33]
	v_pk_mul_f32 v[10:11], v[30:31], v[30:31]
	v_fmac_f32_e32 v26, 0xba000000, v67
	v_pk_mov_b32 v[12:13], v[10:11], v[8:9] op_sel:[1,0]
	v_mov_b32_e32 v11, v9
	v_fmac_f32_e32 v28, 0xba000000, v67
	v_fmamk_f32 v27, v67, 0xba000000, v27
	v_mul_f32_e32 v0, v26, v26
	v_pk_add_f32 v[8:9], v[12:13], v[10:11]
	v_fmamk_f32 v29, v67, 0xba000000, v29
	v_fmac_f32_e32 v22, 0xba000000, v99
	v_pk_fma_f32 v[10:11], v[26:27], v[26:27], v[0:1] op_sel_hi:[1,1,0]
	v_mul_f32_e32 v0, v28, v28
	v_pk_add_f32 v[2:3], v[2:3], v[2:3] op_sel_hi:[0,1]
	v_pk_add_f32 v[6:7], v[6:7], v[6:7] op_sel_hi:[0,1]
	v_fmac_f32_e32 v24, 0xba000000, v99
	v_fmamk_f32 v23, v99, 0xba000000, v23
	v_pk_fma_f32 v[12:13], v[28:29], v[28:29], v[0:1] op_sel_hi:[1,1,0]
	v_mul_f32_e32 v0, v22, v22
	v_fmamk_f32 v15, v67, 0xba000000, v15
	v_fmac_f32_e32 v14, 0xba000000, v67
	v_fmamk_f32 v21, v67, 0xba000000, v21
	v_fmac_f32_e32 v20, 0xba000000, v67
	v_fmamk_f32 v25, v99, 0xba000000, v25
	v_pk_fma_f32 v[120:121], v[22:23], v[22:23], v[0:1] op_sel_hi:[1,1,0]
	v_mul_f32_e32 v0, v24, v24
	v_mul_f32_e32 v10, v20, v20
	v_mul_f32_e32 v12, v21, v21
	v_mul_f32_e32 v2, v14, v14
	v_mul_f32_e32 v6, v15, v15
	v_pk_add_f32 v[4:5], v[4:5], v[4:5] op_sel_hi:[0,1]
	v_pk_add_f32 v[8:9], v[8:9], v[8:9] op_sel_hi:[0,1]
	v_pk_fma_f32 v[128:129], v[24:25], v[24:25], v[0:1] op_sel_hi:[1,1,0]
	v_fmamk_f32 v17, v99, 0xba000000, v17
	v_fmac_f32_e32 v16, 0xba000000, v99
	v_fmamk_f32 v19, v99, 0xba000000, v19
	v_fmac_f32_e32 v18, 0xba000000, v99
	v_pk_add_f32 v[10:11], v[10:11], v[12:13]
	v_pk_add_f32 v[2:3], v[6:7], v[2:3]
	v_mul_f32_e32 v120, v18, v18
	v_pk_add_f32 v[2:3], v[10:11], v[2:3]
	v_mul_f32_e32 v128, v19, v19
	v_mul_f32_e32 v8, v16, v16
	v_mul_f32_e32 v4, v17, v17
	v_add_f32_e32 v0, v2, v3
	v_pk_add_f32 v[2:3], v[120:121], v[128:129]
	v_pk_add_f32 v[4:5], v[8:9], v[4:5]
	v_lshl_add_u64 v[120:121], v[100:101], 0, v[94:95]
	v_pk_add_f32 v[2:3], v[2:3], v[4:5]
	s_nop 0
	v_add_f32_e32 v2, v2, v3
	ds_bpermute_b32 v3, v142, v0
	s_waitcnt lgkmcnt(0)
; __device__ __forceinline__ unsigned pk2(float lo, float hi) { return f2bf(lo) | (f2bf(hi) << 16); }
; __device__ __forceinline__ void ln_phase(const Params& p, const int layer, const int row_lo, const int row_hi, const int wg_id, const int n_wg) {
;     ...
;         const float rstd0 = 1.f / sqrtf(wave_sum(q0) * (1.f / DM) + LN_EPS), rstd1 = 1.f / sqrtf(wave_sum(q1) * (1.f / DM) + LN_EPS);
;         f32x4* zr0 = (f32x4*)(Z + (size_t)m0 * DM) + lane; f32x4* zr1 = (f32x4*)(Z + (size_t)m1 * DM) + lane;
;         unsigned long long* o80 = (unsigned long long*)(XB + (size_t)m0 * DM) + lane; unsigned long long* o81 = (unsigned long long*)(XB + (size_t)m1 * DM) + lane;
; #pragma unroll
;         for (int j = 0; j < 8; ++j) { const f32x4 gv = *((const f32x4*)g + lane + 64 * j), bv = *((const f32x4*)bb + lane + 64 * j);
;             const f32x4 y0 = v0[j] * rstd0 * gv + bv, y1 = v1[j] * rstd1 * gv + bv;
;             if (layer == 0) { o80[64 * j] = (unsigned long long)pk2(y0.x, y0.y) | ((unsigned long long)pk2(y0.z, y0.w) << 32);
;                 if (ok1) o81[64 * j] = (unsigned long long)pk2(y1.x, y1.y) | ((unsigned long long)pk2(y1.z, y1.w) << 32); }
;             else { zr0[64 * j] = y0; if (ok1) zr1[64 * j] = y1; } }
	v_add_f32_e32 v0, v0, v3
	ds_bpermute_b32 v3, v143, v0
	s_waitcnt lgkmcnt(0)
	v_add_f32_e32 v0, v0, v3
	ds_bpermute_b32 v3, v144, v0
	s_waitcnt lgkmcnt(0)
	v_add_f32_e32 v0, v0, v3
	ds_bpermute_b32 v3, v145, v0
	s_waitcnt lgkmcnt(0)
	v_add_f32_e32 v0, v0, v3
	ds_bpermute_b32 v3, v146, v0
	s_waitcnt lgkmcnt(0)
	v_add_f32_e32 v0, v0, v3
	ds_bpermute_b32 v3, v147, v0
	s_waitcnt lgkmcnt(0)
	v_add_f32_e32 v0, v0, v3
	v_fmamk_f32 v0, v0, 0x3a000000, v218
	v_cmp_gt_f32_e32 vcc, s2, v0
	v_mul_f32_e32 v3, 0x4f800000, v0
	s_nop 0
	v_cndmask_b32_e32 v0, v0, v3, vcc
	v_sqrt_f32_e32 v3, v0
	s_nop 0
	v_add_u32_e32 v4, -1, v3
	v_fma_f32 v5, -v4, v3, v0
	v_cmp_ge_f32_e64 s[0:1], 0, v5
	v_add_u32_e32 v5, 1, v3
	s_nop 0
	v_cndmask_b32_e64 v4, v3, v4, s[0:1]
	v_fma_f32 v3, -v5, v3, v0
	v_cmp_lt_f32_e64 s[0:1], 0, v3
	s_nop 1
	v_cndmask_b32_e64 v3, v4, v5, s[0:1]
	v_mul_f32_e32 v4, 0x37800000, v3
	v_cndmask_b32_e32 v3, v3, v4, vcc
	v_cmp_class_f32_e32 vcc, v0, v219
	s_nop 1
	v_cndmask_b32_e32 v0, v3, v0, vcc
	v_div_scale_f32 v3, s[0:1], v0, v0, 1.0
	v_rcp_f32_e32 v4, v3
	s_nop 0
	v_fma_f32 v5, -v3, v4, 1.0
	v_fmac_f32_e32 v4, v5, v4
	v_div_scale_f32 v5, vcc, 1.0, v0, 1.0
	v_mul_f32_e32 v6, v5, v4
	v_fma_f32 v7, -v3, v6, v5
	v_fmac_f32_e32 v6, v7, v4
	v_fma_f32 v3, -v3, v6, v5
	v_div_fmas_f32 v3, v3, v4, v6
	v_div_fixup_f32 v118, v3, v0, 1.0
	ds_bpermute_b32 v0, v142, v2
	v_pk_mul_f32 v[10:11], v[116:117], v[118:119] op_sel_hi:[1,0]
	v_pk_mul_f32 v[12:13], v[114:115], v[118:119] op_sel_hi:[1,0]
	s_waitcnt lgkmcnt(0)
	v_add_f32_e32 v0, v2, v0
	ds_bpermute_b32 v2, v143, v0
	s_waitcnt lgkmcnt(0)
	v_add_f32_e32 v0, v0, v2
	ds_bpermute_b32 v2, v144, v0
	s_waitcnt lgkmcnt(0)
	v_add_f32_e32 v0, v0, v2
	ds_bpermute_b32 v2, v145, v0
	s_waitcnt lgkmcnt(0)
	v_add_f32_e32 v0, v0, v2
	ds_bpermute_b32 v2, v146, v0
	s_waitcnt lgkmcnt(0)
	v_add_f32_e32 v0, v0, v2
	ds_bpermute_b32 v2, v147, v0
	s_waitcnt lgkmcnt(0)
	v_add_f32_e32 v0, v0, v2
	v_fmamk_f32 v0, v0, 0x3a000000, v218
	v_cmp_gt_f32_e32 vcc, s2, v0
	v_mul_f32_e32 v2, 0x4f800000, v0
	s_nop 0
	v_cndmask_b32_e32 v0, v0, v2, vcc
	v_sqrt_f32_e32 v2, v0
	s_nop 0
	v_add_u32_e32 v3, -1, v2
	v_fma_f32 v4, -v3, v2, v0
	v_cmp_ge_f32_e64 s[0:1], 0, v4
	v_add_u32_e32 v4, 1, v2
	s_nop 0
	v_cndmask_b32_e64 v3, v2, v3, s[0:1]
	v_fma_f32 v2, -v4, v2, v0
	v_cmp_lt_f32_e64 s[0:1], 0, v2
	s_nop 1
	v_cndmask_b32_e64 v2, v3, v4, s[0:1]
	v_mul_f32_e32 v3, 0x37800000, v2
	v_cndmask_b32_e32 v2, v2, v3, vcc
	v_cmp_class_f32_e32 vcc, v0, v219
	s_nop 1
	v_cndmask_b32_e32 v0, v2, v0, vcc
	v_div_scale_f32 v2, s[0:1], v0, v0, 1.0
	v_rcp_f32_e32 v3, v2
	s_mov_b64 s[0:1], -1
	v_fma_f32 v4, -v2, v3, 1.0
	v_fmac_f32_e32 v3, v4, v3
	v_div_scale_f32 v4, vcc, 1.0, v0, 1.0
	v_mul_f32_e32 v5, v4, v3
	v_fma_f32 v6, -v2, v5, v4
	v_fmac_f32_e32 v5, v6, v3
	v_fma_f32 v2, -v2, v5, v4
	v_div_fmas_f32 v2, v2, v3, v5
	v_div_fixup_f32 v122, v2, v0, 1.0
	v_mov_b64_e32 v[2:3], v[152:153]
	v_mov_b64_e32 v[4:5], v[154:155]
	v_mov_b64_e32 v[6:7], v[156:157]
	v_mov_b64_e32 v[8:9], v[158:159]
	v_pk_mul_f32 v[112:113], v[112:113], v[122:123] op_sel_hi:[1,0]
	v_pk_mul_f32 v[110:111], v[110:111], v[122:123] op_sel_hi:[1,0]
	s_and_b64 vcc, exec, s[10:11]
	v_pk_fma_f32 v[12:13], v[4:5], v[12:13], v[8:9]
	v_pk_fma_f32 v[10:11], v[2:3], v[10:11], v[6:7]
	v_pk_fma_f32 v[4:5], v[4:5], v[110:111], v[8:9]
	v_pk_fma_f32 v[2:3], v[2:3], v[112:113], v[6:7]
	s_cbranch_vccz .LBB0_1037
	global_store_dwordx4 v[120:121], v[10:13], off
	s_and_saveexec_b64 s[0:1], s[38:39]
	s_cbranch_execz .LBB0_1036
	global_store_dwordx4 v[102:103], v[2:5], off

; __device__ __forceinline__ unsigned pk2(float lo, float hi) { return f2bf(lo) | (f2bf(hi) << 16); }
; __device__ __forceinline__ void ln_phase(const Params& p, const int layer, const int row_lo, const int row_hi, const int wg_id, const int n_wg) {
;     ...
;         for (int j = 0; j < 8; ++j) { const f32x4 gv = *((const f32x4*)g + lane + 64 * j), bv = *((const f32x4*)bb + lane + 64 * j);
;             const f32x4 y0 = v0[j] * rstd0 * gv + bv, y1 = v1[j] * rstd1 * gv + bv;
;             if (layer == 0) { o80[64 * j] = (unsigned long long)pk2(y0.x, y0.y) | ((unsigned long long)pk2(y0.z, y0.w) << 32);
;                 if (ok1) o81[64 * j] = (unsigned long long)pk2(y1.x, y1.y) | ((unsigned long long)pk2(y1.z, y1.w) << 32); }
;             else { zr0[64 * j] = y0; if (ok1) zr1[64 * j] = y1; } }
.LBB0_1041:
	v_mov_b64_e32 v[6:7], v[160:161]
	v_mov_b64_e32 v[8:9], v[162:163]
	v_mov_b64_e32 v[10:11], v[168:169]
	v_mov_b64_e32 v[12:13], v[170:171]
	v_mov_b32_e32 v55, v119
	v_mov_b32_e32 v119, v118
	v_mov_b32_e32 v2, v118
	v_mov_b32_e32 v3, v118
	v_mov_b32_e32 v57, v127
	v_pk_mul_f32 v[2:3], v[56:57], v[2:3]
	v_pk_mul_f32 v[54:55], v[54:55], v[118:119]
	v_mov_b32_e32 v51, v123
	v_mov_b32_e32 v123, v122
	v_mov_b32_e32 v53, v125
	v_pk_mul_f32 v[50:51], v[50:51], v[122:123]
	v_cndmask_b32_e64 v0, 0, 1, s[10:11]
	s_mov_b64 s[0:1], -1
	v_cmp_ne_u32_e64 s[40:41], 1, v0
	s_andn2_b64 vcc, exec, s[10:11]
	v_pk_fma_f32 v[4:5], v[2:3], v[8:9], v[12:13]
	v_pk_fma_f32 v[2:3], v[54:55], v[6:7], v[10:11]
	v_mov_b32_e32 v54, v122
	v_mov_b32_e32 v55, v122
	v_pk_mul_f32 v[52:53], v[52:53], v[54:55]
	v_pk_fma_f32 v[6:7], v[50:51], v[6:7], v[10:11]
	v_pk_fma_f32 v[8:9], v[52:53], v[8:9], v[12:13]
	s_cbranch_vccnz .LBB0_1045
	global_store_dwordx4 v[120:121], v[2:5], off offset:1024
	s_and_saveexec_b64 s[0:1], s[38:39]
	s_cbranch_execz .LBB0_1044
	global_store_dwordx4 v[102:103], v[6:9], off offset:1024

; __device__ __forceinline__ unsigned pk2(float lo, float hi) { return f2bf(lo) | (f2bf(hi) << 16); }
; __device__ __forceinline__ void ln_phase(const Params& p, const int layer, const int row_lo, const int row_hi, const int wg_id, const int n_wg) {
;     ...
;         for (int j = 0; j < 8; ++j) { const f32x4 gv = *((const f32x4*)g + lane + 64 * j), bv = *((const f32x4*)bb + lane + 64 * j);
;             const f32x4 y0 = v0[j] * rstd0 * gv + bv, y1 = v1[j] * rstd1 * gv + bv;
;             if (layer == 0) { o80[64 * j] = (unsigned long long)pk2(y0.x, y0.y) | ((unsigned long long)pk2(y0.z, y0.w) << 32);
;                 if (ok1) o81[64 * j] = (unsigned long long)pk2(y1.x, y1.y) | ((unsigned long long)pk2(y1.z, y1.w) << 32); }
;             else { zr0[64 * j] = y0; if (ok1) zr1[64 * j] = y1; } }
.LBB0_1049:
	v_mov_b64_e32 v[2:3], v[172:173]
	v_mov_b64_e32 v[4:5], v[174:175]
	v_mov_b64_e32 v[10:11], v[176:177]
	v_mov_b64_e32 v[12:13], v[178:179]
	v_mov_b32_e32 v6, v118
	v_mov_b32_e32 v7, v118
	v_pk_mul_f32 v[6:7], v[48:49], v[6:7]
	v_pk_mul_f32 v[46:47], v[46:47], v[118:119]
	v_pk_mul_f32 v[48:49], v[106:107], v[122:123]
	s_mov_b64 s[0:1], -1
	s_and_b64 vcc, exec, s[40:41]
	v_pk_fma_f32 v[8:9], v[6:7], v[4:5], v[12:13]
	v_pk_fma_f32 v[6:7], v[46:47], v[2:3], v[10:11]
	v_mov_b32_e32 v46, v122
	v_mov_b32_e32 v47, v122
	v_pk_mul_f32 v[46:47], v[108:109], v[46:47]
	v_pk_fma_f32 v[2:3], v[48:49], v[2:3], v[10:11]
	v_pk_fma_f32 v[4:5], v[46:47], v[4:5], v[12:13]
	s_cbranch_vccnz .LBB0_1053
	global_store_dwordx4 v[120:121], v[6:9], off offset:2048
	s_and_saveexec_b64 s[0:1], s[38:39]
	s_cbranch_execz .LBB0_1052
	global_store_dwordx4 v[102:103], v[2:5], off offset:2048

; __device__ __forceinline__ unsigned pk2(float lo, float hi) { return f2bf(lo) | (f2bf(hi) << 16); }
; __device__ __forceinline__ void ln_phase(const Params& p, const int layer, const int row_lo, const int row_hi, const int wg_id, const int n_wg) {
;     ...
;         for (int j = 0; j < 8; ++j) { const f32x4 gv = *((const f32x4*)g + lane + 64 * j), bv = *((const f32x4*)bb + lane + 64 * j);
;             const f32x4 y0 = v0[j] * rstd0 * gv + bv, y1 = v1[j] * rstd1 * gv + bv;
;             if (layer == 0) { o80[64 * j] = (unsigned long long)pk2(y0.x, y0.y) | ((unsigned long long)pk2(y0.z, y0.w) << 32);
;                 if (ok1) o81[64 * j] = (unsigned long long)pk2(y1.x, y1.y) | ((unsigned long long)pk2(y1.z, y1.w) << 32); }
;             else { zr0[64 * j] = y0; if (ok1) zr1[64 * j] = y1; } }
.LBB0_1057:
	v_mov_b64_e32 v[2:3], v[180:181]
	v_mov_b64_e32 v[4:5], v[182:183]
	v_mov_b64_e32 v[10:11], v[184:185]
	v_mov_b64_e32 v[12:13], v[186:187]
	v_mov_b32_e32 v6, v118
	v_mov_b32_e32 v7, v118
	v_pk_mul_f32 v[6:7], v[64:65], v[6:7]
	v_pk_mul_f32 v[46:47], v[62:63], v[118:119]
	v_pk_mul_f32 v[48:49], v[58:59], v[122:123]
	s_mov_b64 s[0:1], -1
	s_and_b64 vcc, exec, s[40:41]
	v_pk_fma_f32 v[8:9], v[6:7], v[4:5], v[12:13]
	v_pk_fma_f32 v[6:7], v[46:47], v[2:3], v[10:11]
	v_mov_b32_e32 v46, v122
	v_mov_b32_e32 v47, v122
	v_pk_mul_f32 v[46:47], v[60:61], v[46:47]
	v_pk_fma_f32 v[2:3], v[48:49], v[2:3], v[10:11]
	v_pk_fma_f32 v[4:5], v[46:47], v[4:5], v[12:13]
	s_cbranch_vccnz .LBB0_1061
	global_store_dwordx4 v[120:121], v[6:9], off offset:3072
	s_and_saveexec_b64 s[0:1], s[38:39]
	s_cbranch_execz .LBB0_1060
	global_store_dwordx4 v[102:103], v[2:5], off offset:3072

; __device__ __forceinline__ unsigned pk2(float lo, float hi) { return f2bf(lo) | (f2bf(hi) << 16); }
; __device__ __forceinline__ void ln_phase(const Params& p, const int layer, const int row_lo, const int row_hi, const int wg_id, const int n_wg) {
;     ...
;         for (int j = 0; j < 8; ++j) { const f32x4 gv = *((const f32x4*)g + lane + 64 * j), bv = *((const f32x4*)bb + lane + 64 * j);
;             const f32x4 y0 = v0[j] * rstd0 * gv + bv, y1 = v1[j] * rstd1 * gv + bv;
;             if (layer == 0) { o80[64 * j] = (unsigned long long)pk2(y0.x, y0.y) | ((unsigned long long)pk2(y0.z, y0.w) << 32);
;                 if (ok1) o81[64 * j] = (unsigned long long)pk2(y1.x, y1.y) | ((unsigned long long)pk2(y1.z, y1.w) << 32); }
;             else { zr0[64 * j] = y0; if (ok1) zr1[64 * j] = y1; } }
.LBB0_1065:
	v_mov_b64_e32 v[2:3], v[188:189]
	v_mov_b64_e32 v[4:5], v[190:191]
	v_mov_b64_e32 v[10:11], v[196:197]
	v_mov_b64_e32 v[12:13], v[198:199]
	v_mov_b32_e32 v6, v118
	v_mov_b32_e32 v7, v118
	v_pk_mul_f32 v[6:7], v[44:45], v[6:7]
	v_pk_mul_f32 v[42:43], v[42:43], v[118:119]
	v_pk_mul_f32 v[38:39], v[38:39], v[122:123]
	s_mov_b64 s[0:1], -1
	s_and_b64 vcc, exec, s[40:41]
	v_pk_fma_f32 v[8:9], v[6:7], v[4:5], v[12:13]
	v_pk_fma_f32 v[6:7], v[42:43], v[2:3], v[10:11]
	v_mov_b32_e32 v42, v122
	v_mov_b32_e32 v43, v122
	v_pk_mul_f32 v[40:41], v[40:41], v[42:43]
	v_pk_fma_f32 v[2:3], v[38:39], v[2:3], v[10:11]
	v_pk_fma_f32 v[4:5], v[40:41], v[4:5], v[12:13]
	s_cbranch_vccnz .LBB0_1069
	v_add_co_u32_e32 v10, vcc, 0x1000, v120
	s_nop 1
	v_addc_co_u32_e32 v11, vcc, 0, v121, vcc
	global_store_dwordx4 v[10:11], v[6:9], off
	s_and_saveexec_b64 s[0:1], s[38:39]
	s_cbranch_execz .LBB0_1068
	v_add_co_u32_e32 v10, vcc, 0x1000, v102
	s_nop 1
	v_addc_co_u32_e32 v11, vcc, 0, v103, vcc
	global_store_dwordx4 v[10:11], v[2:5], off

; __device__ __forceinline__ unsigned pk2(float lo, float hi) { return f2bf(lo) | (f2bf(hi) << 16); }
; __device__ __forceinline__ void ln_phase(const Params& p, const int layer, const int row_lo, const int row_hi, const int wg_id, const int n_wg) {
;     ...
;         for (int j = 0; j < 8; ++j) { const f32x4 gv = *((const f32x4*)g + lane + 64 * j), bv = *((const f32x4*)bb + lane + 64 * j);
;             const f32x4 y0 = v0[j] * rstd0 * gv + bv, y1 = v1[j] * rstd1 * gv + bv;
;             if (layer == 0) { o80[64 * j] = (unsigned long long)pk2(y0.x, y0.y) | ((unsigned long long)pk2(y0.z, y0.w) << 32);
;                 if (ok1) o81[64 * j] = (unsigned long long)pk2(y1.x, y1.y) | ((unsigned long long)pk2(y1.z, y1.w) << 32); }
;             else { zr0[64 * j] = y0; if (ok1) zr1[64 * j] = y1; } }
.LBB0_1073:
	v_mov_b64_e32 v[2:3], v[210:211]
	v_mov_b64_e32 v[4:5], v[212:213]
	v_mov_b64_e32 v[10:11], v[224:225]
	v_mov_b64_e32 v[12:13], v[226:227]
	v_mov_b32_e32 v6, v118
	v_mov_b32_e32 v7, v118
	v_pk_mul_f32 v[6:7], v[36:37], v[6:7]
	v_pk_mul_f32 v[34:35], v[34:35], v[118:119]
	v_pk_mul_f32 v[30:31], v[30:31], v[122:123]
	s_mov_b64 s[0:1], -1
	s_and_b64 vcc, exec, s[40:41]
	v_pk_fma_f32 v[8:9], v[6:7], v[4:5], v[12:13]
	v_pk_fma_f32 v[6:7], v[34:35], v[2:3], v[10:11]
	v_mov_b32_e32 v34, v122
	v_mov_b32_e32 v35, v122
	v_pk_mul_f32 v[32:33], v[32:33], v[34:35]
	v_pk_fma_f32 v[2:3], v[30:31], v[2:3], v[10:11]
	v_pk_fma_f32 v[4:5], v[32:33], v[4:5], v[12:13]
	s_cbranch_vccnz .LBB0_1077
	v_add_co_u32_e32 v10, vcc, 0x1000, v120
	s_nop 1
	v_addc_co_u32_e32 v11, vcc, 0, v121, vcc
	global_store_dwordx4 v[10:11], v[6:9], off offset:1024
	s_and_saveexec_b64 s[0:1], s[38:39]
	s_cbranch_execz .LBB0_1076
	v_add_co_u32_e32 v10, vcc, 0x1000, v102
	s_nop 1
	v_addc_co_u32_e32 v11, vcc, 0, v103, vcc
	global_store_dwordx4 v[10:11], v[2:5], off offset:1024

; __device__ __forceinline__ unsigned pk2(float lo, float hi) { return f2bf(lo) | (f2bf(hi) << 16); }
; __device__ __forceinline__ void ln_phase(const Params& p, const int layer, const int row_lo, const int row_hi, const int wg_id, const int n_wg) {
;     ...
;         for (int j = 0; j < 8; ++j) { const f32x4 gv = *((const f32x4*)g + lane + 64 * j), bv = *((const f32x4*)bb + lane + 64 * j);
;             const f32x4 y0 = v0[j] * rstd0 * gv + bv, y1 = v1[j] * rstd1 * gv + bv;
;             if (layer == 0) { o80[64 * j] = (unsigned long long)pk2(y0.x, y0.y) | ((unsigned long long)pk2(y0.z, y0.w) << 32);
;                 if (ok1) o81[64 * j] = (unsigned long long)pk2(y1.x, y1.y) | ((unsigned long long)pk2(y1.z, y1.w) << 32); }
;             else { zr0[64 * j] = y0; if (ok1) zr1[64 * j] = y1; } }
.LBB0_1081:
	v_mov_b64_e32 v[2:3], v[228:229]
	v_mov_b64_e32 v[4:5], v[230:231]
	v_mov_b64_e32 v[10:11], v[232:233]
	v_mov_b64_e32 v[12:13], v[234:235]
	v_mov_b32_e32 v6, v118
	v_mov_b32_e32 v7, v118
	v_pk_mul_f32 v[6:7], v[28:29], v[6:7]
	v_pk_mul_f32 v[26:27], v[26:27], v[118:119]
	v_pk_mul_f32 v[22:23], v[22:23], v[122:123]
	s_mov_b64 s[0:1], -1
	s_and_b64 vcc, exec, s[40:41]
	v_pk_fma_f32 v[8:9], v[6:7], v[4:5], v[12:13]
	v_pk_fma_f32 v[6:7], v[26:27], v[2:3], v[10:11]
	v_mov_b32_e32 v26, v122
	v_mov_b32_e32 v27, v122
	v_pk_mul_f32 v[24:25], v[24:25], v[26:27]
	v_pk_fma_f32 v[2:3], v[22:23], v[2:3], v[10:11]
	v_pk_fma_f32 v[4:5], v[24:25], v[4:5], v[12:13]
	s_cbranch_vccnz .LBB0_1085
	v_add_co_u32_e32 v10, vcc, 0x1000, v120
	s_nop 1
	v_addc_co_u32_e32 v11, vcc, 0, v121, vcc
	global_store_dwordx4 v[10:11], v[6:9], off offset:2048
	s_and_saveexec_b64 s[0:1], s[38:39]
	s_cbranch_execz .LBB0_1084
	v_add_co_u32_e32 v10, vcc, 0x1000, v102
	s_nop 1
	v_addc_co_u32_e32 v11, vcc, 0, v103, vcc
	global_store_dwordx4 v[10:11], v[2:5], off offset:2048

; __device__ __forceinline__ unsigned pk2(float lo, float hi) { return f2bf(lo) | (f2bf(hi) << 16); }
; __device__ __forceinline__ void ln_phase(const Params& p, const int layer, const int row_lo, const int row_hi, const int wg_id, const int n_wg) {
;     ...
;         for (int j = 0; j < 8; ++j) { const f32x4 gv = *((const f32x4*)g + lane + 64 * j), bv = *((const f32x4*)bb + lane + 64 * j);
;             const f32x4 y0 = v0[j] * rstd0 * gv + bv, y1 = v1[j] * rstd1 * gv + bv;
;             if (layer == 0) { o80[64 * j] = (unsigned long long)pk2(y0.x, y0.y) | ((unsigned long long)pk2(y0.z, y0.w) << 32);
;                 if (ok1) o81[64 * j] = (unsigned long long)pk2(y1.x, y1.y) | ((unsigned long long)pk2(y1.z, y1.w) << 32); }
;             else { zr0[64 * j] = y0; if (ok1) zr1[64 * j] = y1; } }
.LBB0_1089:
	v_mov_b64_e32 v[2:3], v[236:237]
	v_mov_b64_e32 v[4:5], v[238:239]
	v_mov_b64_e32 v[10:11], v[244:245]
	v_mov_b64_e32 v[12:13], v[246:247]
	v_mov_b32_e32 v6, v118
	v_mov_b32_e32 v7, v118
	v_mov_b32_e32 v8, v122
	v_mov_b32_e32 v9, v122
	v_pk_mul_f32 v[20:21], v[20:21], v[118:119]
	v_pk_mul_f32 v[18:19], v[18:19], v[122:123]
	v_pk_mul_f32 v[6:7], v[14:15], v[6:7]
	v_pk_mul_f32 v[14:15], v[16:17], v[8:9]
	s_and_b64 vcc, exec, s[40:41]
	s_mov_b64 s[0:1], -1
	v_pk_fma_f32 v[8:9], v[6:7], v[4:5], v[12:13]
	v_pk_fma_f32 v[6:7], v[20:21], v[2:3], v[10:11]
	v_pk_fma_f32 v[4:5], v[14:15], v[4:5], v[12:13]
	v_pk_fma_f32 v[2:3], v[18:19], v[2:3], v[10:11]
	s_cbranch_vccnz .LBB0_1093
	v_add_co_u32_e32 v10, vcc, 0x1000, v120
	s_nop 1
	v_addc_co_u32_e32 v11, vcc, 0, v121, vcc
	global_store_dwordx4 v[10:11], v[6:9], off offset:3072
	s_and_saveexec_b64 s[0:1], s[38:39]
	s_cbranch_execz .LBB0_1092
	v_add_co_u32_e32 v10, vcc, 0x1000, v102
	s_nop 1
	v_addc_co_u32_e32 v11, vcc, 0, v103, vcc
	global_store_dwordx4 v[10:11], v[2:5], off offset:3072

; __global__ void __launch_bounds__(NTHR, 2) hybrid_fwd(Params p) {
	.amdhsa_kernel _Z10hybrid_fwd6Params
		.amdhsa_group_segment_fixed_size 0
		.amdhsa_private_segment_fixed_size 0
		.amdhsa_kernarg_size 448
		.amdhsa_user_sgpr_count 2
		.amdhsa_user_sgpr_dispatch_ptr 0
		.amdhsa_user_sgpr_queue_ptr 0
		.amdhsa_user_sgpr_kernarg_segment_ptr 1
		.amdhsa_user_sgpr_dispatch_id 0
		.amdhsa_user_sgpr_kernarg_preload_length 0
		.amdhsa_user_sgpr_kernarg_preload_offset 0
		.amdhsa_user_sgpr_private_segment_size 0
		.amdhsa_uses_dynamic_stack 0
		.amdhsa_enable_private_segment 0
		.amdhsa_system_sgpr_workgroup_id_x 1
		.amdhsa_system_sgpr_workgroup_id_y 0
		.amdhsa_system_sgpr_workgroup_id_z 0
		.amdhsa_system_sgpr_workgroup_info 0
		.amdhsa_system_vgpr_workitem_id 2
		.amdhsa_next_free_vgpr 256
		.amdhsa_next_free_sgpr 102
		.amdhsa_accum_offset 256
		.amdhsa_reserve_vcc 1
		.amdhsa_float_round_mode_32 0
		.amdhsa_float_round_mode_16_64 0
		.amdhsa_float_denorm_mode_32 3
		.amdhsa_float_denorm_mode_16_64 3
		.amdhsa_dx10_clamp 1
		.amdhsa_ieee_mode 1
		.amdhsa_fp16_overflow 0
		.amdhsa_tg_split 0
		.amdhsa_exception_fp_ieee_invalid_op 0
		.amdhsa_exception_fp_denorm_src 0
		.amdhsa_exception_fp_ieee_div_zero 0
		.amdhsa_exception_fp_ieee_overflow 0
		.amdhsa_exception_fp_ieee_underflow 0
		.amdhsa_exception_fp_ieee_inexact 0
		.amdhsa_exception_int_div_zero 0
	.end_amdhsa_kernel

; __global__ void __launch_bounds__(NTHR, 2) hybrid_fwd(Params p) {
amdhsa.kernels:
  - .agpr_count:     0
    .args:
      - .offset:         0
        .size:           192
        .value_kind:     by_value
      - .offset:         192
        .size:           4
        .value_kind:     hidden_block_count_x
      - .offset:         196
        .size:           4
        .value_kind:     hidden_block_count_y
      - .offset:         200
        .size:           4
        .value_kind:     hidden_block_count_z
      - .offset:         204
        .size:           2
        .value_kind:     hidden_group_size_x
      - .offset:         206
        .size:           2
        .value_kind:     hidden_group_size_y
      - .offset:         208
        .size:           2
        .value_kind:     hidden_group_size_z
      - .offset:         210
        .size:           2
        .value_kind:     hidden_remainder_x
      - .offset:         212
        .size:           2
        .value_kind:     hidden_remainder_y
      - .offset:         214
        .size:           2
        .value_kind:     hidden_remainder_z
      - .offset:         232
        .size:           8
        .value_kind:     hidden_global_offset_x
      - .offset:         240
        .size:           8
        .value_kind:     hidden_global_offset_y
      - .offset:         248
        .size:           8
        .value_kind:     hidden_global_offset_z
      - .offset:         256
        .size:           2
        .value_kind:     hidden_grid_dims
      - .offset:         280
        .size:           8
        .value_kind:     hidden_multigrid_sync_arg
      - .offset:         312
        .size:           4
        .value_kind:     hidden_dynamic_lds_size
    .group_segment_fixed_size: 0
    .kernarg_segment_align: 8
    .kernarg_segment_size: 448
    .language:       OpenCL C
    .language_version:
      - 2
      - 0
    .max_flat_workgroup_size: 512
    .name:           _Z10hybrid_fwd6Params
    .private_segment_fixed_size: 0
    .sgpr_count:     108
    .sgpr_spill_count: 241
    .symbol:         _Z10hybrid_fwd6Params.kd
    .uniform_work_group_size: 1
    .uses_dynamic_stack: false
    .vgpr_count:     256
    .vgpr_spill_count: 0
    .wavefront_size: 64
